# in-proj epilogue: paired 16-byte bf16 stores via permlane16_swap (proj and head-major K/V copies), dead proj K/V stores of prompt rows skipped
# speedup vs baseline: 1.3478x; 1.3478x over previous
.LBB0_316:
	ds_read_b128 v[148:151], v163
	ds_read_b128 v[152:155], v163 offset:1024
	ds_read_b128 v[158:161], v163 offset:2048
	ds_read_b128 v[166:169], v163 offset:3072
	s_add_u32 s10, s8, 0xfff80080
	s_addc_u32 s11, s9, -1
	s_cmp_eq_u32 s57, 28
	s_cselect_b32 s51, s7, s11
	s_cselect_b32 s50, s45, s10
	s_cselect_b32 s59, s53, s56
	s_cselect_b32 s58, s54, s55
	v_lshl_add_u64 v[202:203], s[8:9], 0, v[138:139]
	s_add_i32 m0, s67, 0xc000
	ds_read_b128 v[170:173], v164
	ds_read_b128 v[174:177], v164 offset:1024
	ds_read_b128 v[178:181], v164 offset:2048
	ds_read_b128 v[182:185], v164 offset:3072
	ds_read_b128 v[186:189], v164 offset:4096
	ds_read_b128 v[190:193], v164 offset:5120
	ds_read_b128 v[194:197], v164 offset:6144
	ds_read_b128 v[198:201], v164 offset:7168
	global_load_lds_dwordx4 v[202:203], off
	v_lshl_add_u64 v[202:203], s[8:9], 0, v[140:141]
	s_add_i32 m0, s67, 0xe000
	s_nop 0
	global_load_lds_dwordx4 v[202:203], off
	s_waitcnt lgkmcnt(8)
	s_barrier
	s_waitcnt lgkmcnt(0)
	s_setprio 1
	s_waitcnt lgkmcnt(0)
	v_mfma_f32_16x16x32_bf16 v[124:127], v[148:151], v[170:173], v[124:127]
	v_mfma_f32_16x16x32_bf16 v[120:123], v[158:161], v[170:173], v[120:123]
	v_mfma_f32_16x16x32_bf16 v[108:111], v[148:151], v[178:181], v[108:111]
	v_mfma_f32_16x16x32_bf16 v[104:107], v[158:161], v[178:181], v[104:107]
	v_mfma_f32_16x16x32_bf16 v[92:95], v[148:151], v[186:189], v[92:95]
	v_mfma_f32_16x16x32_bf16 v[88:91], v[158:161], v[186:189], v[88:91]
	v_mfma_f32_16x16x32_bf16 v[76:79], v[148:151], v[194:197], v[76:79]
	v_mfma_f32_16x16x32_bf16 v[72:75], v[158:161], v[194:197], v[72:75]
	v_mfma_f32_16x16x32_bf16 v[124:127], v[152:155], v[174:177], v[124:127]
	v_mfma_f32_16x16x32_bf16 v[120:123], v[166:169], v[174:177], v[120:123]
	v_mfma_f32_16x16x32_bf16 v[108:111], v[152:155], v[182:185], v[108:111]
	v_mfma_f32_16x16x32_bf16 v[104:107], v[166:169], v[182:185], v[104:107]
	v_mfma_f32_16x16x32_bf16 v[92:95], v[152:155], v[190:193], v[92:95]
	v_mfma_f32_16x16x32_bf16 v[88:91], v[166:169], v[190:193], v[88:91]
	v_mfma_f32_16x16x32_bf16 v[76:79], v[152:155], v[198:201], v[76:79]
	v_mfma_f32_16x16x32_bf16 v[72:75], v[166:169], v[198:201], v[72:75]
	s_setprio 0
	s_barrier
	s_add_i32 s10, s82, s66
	v_lshl_add_u64 v[218:219], s[58:59], 0, v[128:129]
	s_mov_b32 m0, s10
	ds_read_b128 v[202:205], v165
	ds_read_b128 v[206:209], v165 offset:1024
	ds_read_b128 v[210:213], v165 offset:2048
	ds_read_b128 v[214:217], v165 offset:3072
	global_load_lds_dwordx4 v[218:219], off
	v_lshl_add_u64 v[220:221], v[218:219], 0, s[12:13]
	s_add_i32 m0, s10, 0x2000
	s_nop 0
	global_load_lds_dwordx4 v[220:221], off
	s_barrier
	s_waitcnt lgkmcnt(0)
	s_setprio 1
	s_waitcnt lgkmcnt(0)
	v_mfma_f32_16x16x32_bf16 v[116:119], v[202:205], v[170:173], v[116:119]
	v_mfma_f32_16x16x32_bf16 v[112:115], v[210:213], v[170:173], v[112:115]
	v_mfma_f32_16x16x32_bf16 v[100:103], v[202:205], v[178:181], v[100:103]
	v_mfma_f32_16x16x32_bf16 v[96:99], v[210:213], v[178:181], v[96:99]
	v_mfma_f32_16x16x32_bf16 v[84:87], v[202:205], v[186:189], v[84:87]
	v_mfma_f32_16x16x32_bf16 v[80:83], v[210:213], v[186:189], v[80:83]
	v_mfma_f32_16x16x32_bf16 v[68:71], v[202:205], v[194:197], v[68:71]
	v_mfma_f32_16x16x32_bf16 v[64:67], v[210:213], v[194:197], v[64:67]
	v_mfma_f32_16x16x32_bf16 v[116:119], v[206:209], v[174:177], v[116:119]
	v_mfma_f32_16x16x32_bf16 v[112:115], v[214:217], v[174:177], v[112:115]
	v_mfma_f32_16x16x32_bf16 v[100:103], v[206:209], v[182:185], v[100:103]
	v_mfma_f32_16x16x32_bf16 v[96:99], v[214:217], v[182:185], v[96:99]
	v_mfma_f32_16x16x32_bf16 v[84:87], v[206:209], v[190:193], v[84:87]
	v_mfma_f32_16x16x32_bf16 v[80:83], v[214:217], v[190:193], v[80:83]
	v_mfma_f32_16x16x32_bf16 v[68:71], v[206:209], v[198:201], v[68:71]
	v_mfma_f32_16x16x32_bf16 v[64:67], v[214:217], v[198:201], v[64:67]
	s_setprio 0
	s_mov_b32 m0, s67
	v_lshl_add_u64 v[220:221], s[50:51], 0, v[130:131]
	s_barrier
	ds_read_b128 v[170:173], v164 offset:16384
	ds_read_b128 v[174:177], v164 offset:17408
	ds_read_b128 v[178:181], v164 offset:18432
	ds_read_b128 v[182:185], v164 offset:19456
	ds_read_b128 v[186:189], v164 offset:20480
	ds_read_b128 v[190:193], v164 offset:21504
	ds_read_b128 v[194:197], v164 offset:22528
	ds_read_b128 v[198:201], v164 offset:23552
	global_load_lds_dwordx4 v[220:221], off
	v_lshl_add_u64 v[222:223], s[50:51], 0, v[132:133]
	s_mov_b32 m0, s68
	s_nop 0
	global_load_lds_dwordx4 v[222:223], off
	s_barrier
	s_waitcnt lgkmcnt(0)
	s_setprio 1
	s_waitcnt lgkmcnt(0)
	v_mfma_f32_16x16x32_bf16 v[60:63], v[148:151], v[170:173], v[60:63]
	v_mfma_f32_16x16x32_bf16 v[56:59], v[158:161], v[170:173], v[56:59]
	v_mfma_f32_16x16x32_bf16 v[44:47], v[148:151], v[178:181], v[44:47]
	v_mfma_f32_16x16x32_bf16 v[40:43], v[158:161], v[178:181], v[40:43]
	v_mfma_f32_16x16x32_bf16 v[28:31], v[148:151], v[186:189], v[28:31]
	v_mfma_f32_16x16x32_bf16 v[24:27], v[158:161], v[186:189], v[24:27]
	v_mfma_f32_16x16x32_bf16 v[12:15], v[148:151], v[194:197], v[12:15]
	v_mfma_f32_16x16x32_bf16 v[8:11], v[158:161], v[194:197], v[8:11]
	v_mfma_f32_16x16x32_bf16 v[60:63], v[152:155], v[174:177], v[60:63]
	v_mfma_f32_16x16x32_bf16 v[56:59], v[166:169], v[174:177], v[56:59]
	v_mfma_f32_16x16x32_bf16 v[44:47], v[152:155], v[182:185], v[44:47]
	v_mfma_f32_16x16x32_bf16 v[40:43], v[166:169], v[182:185], v[40:43]
	v_mfma_f32_16x16x32_bf16 v[28:31], v[152:155], v[190:193], v[28:31]
	v_mfma_f32_16x16x32_bf16 v[24:27], v[166:169], v[190:193], v[24:27]
	v_mfma_f32_16x16x32_bf16 v[12:15], v[152:155], v[198:201], v[12:15]
	v_mfma_f32_16x16x32_bf16 v[8:11], v[166:169], v[198:201], v[8:11]
	s_setprio 0
	s_barrier
	s_add_i32 s10, s83, s66
	v_lshl_add_u64 v[148:149], v[218:219], 0, s[14:15]
	s_mov_b32 m0, s10
	s_nop 0
	global_load_lds_dwordx4 v[148:149], off
	v_lshl_add_u64 v[148:149], v[218:219], 0, s[16:17]
	s_add_i32 m0, s10, 0x2000
	s_nop 0
	global_load_lds_dwordx4 v[148:149], off
	s_waitcnt vmcnt(6)
	s_barrier
	s_setprio 1
	v_mfma_f32_16x16x32_bf16 v[52:55], v[202:205], v[170:173], v[52:55]
	v_mfma_f32_16x16x32_bf16 v[48:51], v[210:213], v[170:173], v[48:51]
	v_mfma_f32_16x16x32_bf16 v[36:39], v[202:205], v[178:181], v[36:39]
	v_mfma_f32_16x16x32_bf16 v[32:35], v[210:213], v[178:181], v[32:35]
	v_mfma_f32_16x16x32_bf16 v[20:23], v[202:205], v[186:189], v[20:23]
	v_mfma_f32_16x16x32_bf16 v[16:19], v[210:213], v[186:189], v[16:19]
	v_mfma_f32_16x16x32_bf16 v[4:7], v[202:205], v[194:197], v[4:7]
	v_mfma_f32_16x16x32_bf16 v[0:3], v[210:213], v[194:197], v[0:3]
	v_mfma_f32_16x16x32_bf16 v[52:55], v[206:209], v[174:177], v[52:55]
	v_mfma_f32_16x16x32_bf16 v[48:51], v[214:217], v[174:177], v[48:51]
	v_mfma_f32_16x16x32_bf16 v[36:39], v[206:209], v[182:185], v[36:39]
	v_mfma_f32_16x16x32_bf16 v[32:35], v[214:217], v[182:185], v[32:35]
	v_mfma_f32_16x16x32_bf16 v[20:23], v[206:209], v[190:193], v[20:23]
	v_mfma_f32_16x16x32_bf16 v[16:19], v[214:217], v[190:193], v[16:19]
	v_mfma_f32_16x16x32_bf16 v[4:7], v[206:209], v[198:201], v[4:7]
	v_mfma_f32_16x16x32_bf16 v[0:3], v[214:217], v[198:201], v[0:3]
	s_setprio 0
	s_add_i32 s10, 0, 0x18000
	v_add_u32_e32 v134, s10, v157
	s_barrier
	ds_read_b128 v[148:151], v134
	ds_read_b128 v[152:155], v134 offset:1024
	ds_read_b128 v[158:161], v134 offset:2048
	ds_read_b128 v[166:169], v134 offset:3072
	s_add_u32 s50, s50, 0x80000
	s_addc_u32 s51, s51, 0
	s_mov_b32 m0, s69
	v_lshl_add_u64 v[202:203], s[50:51], 0, v[130:131]
	ds_read_b128 v[170:173], v164 offset:32768
	ds_read_b128 v[174:177], v164 offset:33792
	ds_read_b128 v[178:181], v164 offset:34816
	ds_read_b128 v[182:185], v164 offset:35840
	ds_read_b128 v[186:189], v164 offset:36864
	ds_read_b128 v[190:193], v164 offset:37888
	ds_read_b128 v[194:197], v164 offset:38912
	ds_read_b128 v[198:201], v164 offset:39936
	global_load_lds_dwordx4 v[202:203], off
	v_lshl_add_u64 v[202:203], s[50:51], 0, v[132:133]
	s_mov_b32 m0, s70
	s_nop 0
	global_load_lds_dwordx4 v[202:203], off
	s_waitcnt lgkmcnt(8)
	s_barrier
	s_waitcnt lgkmcnt(0)
	s_setprio 1
	s_waitcnt lgkmcnt(0)
	v_mfma_f32_16x16x32_bf16 v[124:127], v[148:151], v[170:173], v[124:127]
	v_mfma_f32_16x16x32_bf16 v[120:123], v[158:161], v[170:173], v[120:123]
	v_mfma_f32_16x16x32_bf16 v[108:111], v[148:151], v[178:181], v[108:111]
	v_mfma_f32_16x16x32_bf16 v[104:107], v[158:161], v[178:181], v[104:107]
	v_mfma_f32_16x16x32_bf16 v[92:95], v[148:151], v[186:189], v[92:95]
	v_mfma_f32_16x16x32_bf16 v[88:91], v[158:161], v[186:189], v[88:91]
	v_mfma_f32_16x16x32_bf16 v[76:79], v[148:151], v[194:197], v[76:79]
	v_mfma_f32_16x16x32_bf16 v[72:75], v[158:161], v[194:197], v[72:75]
	v_mfma_f32_16x16x32_bf16 v[124:127], v[152:155], v[174:177], v[124:127]
	v_mfma_f32_16x16x32_bf16 v[120:123], v[166:169], v[174:177], v[120:123]
	v_mfma_f32_16x16x32_bf16 v[108:111], v[152:155], v[182:185], v[108:111]
	v_mfma_f32_16x16x32_bf16 v[104:107], v[166:169], v[182:185], v[104:107]
	v_mfma_f32_16x16x32_bf16 v[92:95], v[152:155], v[190:193], v[92:95]
	v_mfma_f32_16x16x32_bf16 v[88:91], v[166:169], v[190:193], v[88:91]
	v_mfma_f32_16x16x32_bf16 v[76:79], v[152:155], v[198:201], v[76:79]
	v_mfma_f32_16x16x32_bf16 v[72:75], v[166:169], v[198:201], v[72:75]
	s_setprio 0
	s_barrier
	s_add_i32 s11, 0, 0x1c000
	s_add_i32 s10, s10, s66
	v_add_u32_e32 v134, s11, v157
	v_lshl_add_u64 v[224:225], v[218:219], 0, s[26:27]
	s_mov_b32 m0, s10
	ds_read_b128 v[202:205], v134
	ds_read_b128 v[206:209], v134 offset:1024
	ds_read_b128 v[210:213], v134 offset:2048
	ds_read_b128 v[214:217], v134 offset:3072
	global_load_lds_dwordx4 v[224:225], off
	v_lshl_add_u64 v[224:225], v[218:219], 0, s[28:29]
	s_add_i32 m0, s10, 0x2000
	s_nop 0
	global_load_lds_dwordx4 v[224:225], off
	s_barrier
	s_waitcnt lgkmcnt(0)
	s_setprio 1
	s_waitcnt lgkmcnt(0)
	v_mfma_f32_16x16x32_bf16 v[116:119], v[202:205], v[170:173], v[116:119]
	v_mfma_f32_16x16x32_bf16 v[112:115], v[210:213], v[170:173], v[112:115]
	v_mfma_f32_16x16x32_bf16 v[100:103], v[202:205], v[178:181], v[100:103]
	v_mfma_f32_16x16x32_bf16 v[96:99], v[210:213], v[178:181], v[96:99]
	v_mfma_f32_16x16x32_bf16 v[84:87], v[202:205], v[186:189], v[84:87]
	v_mfma_f32_16x16x32_bf16 v[80:83], v[210:213], v[186:189], v[80:83]
	v_mfma_f32_16x16x32_bf16 v[68:71], v[202:205], v[194:197], v[68:71]
	v_mfma_f32_16x16x32_bf16 v[64:67], v[210:213], v[194:197], v[64:67]
	v_mfma_f32_16x16x32_bf16 v[116:119], v[206:209], v[174:177], v[116:119]
	v_mfma_f32_16x16x32_bf16 v[112:115], v[214:217], v[174:177], v[112:115]
	v_mfma_f32_16x16x32_bf16 v[100:103], v[206:209], v[182:185], v[100:103]
	v_mfma_f32_16x16x32_bf16 v[96:99], v[214:217], v[182:185], v[96:99]
	v_mfma_f32_16x16x32_bf16 v[84:87], v[206:209], v[190:193], v[84:87]
	v_mfma_f32_16x16x32_bf16 v[80:83], v[214:217], v[190:193], v[80:83]
	v_mfma_f32_16x16x32_bf16 v[68:71], v[206:209], v[198:201], v[68:71]
	v_mfma_f32_16x16x32_bf16 v[64:67], v[214:217], v[198:201], v[64:67]
	s_setprio 0
	s_mov_b32 m0, s77
	v_lshl_add_u64 v[220:221], v[220:221], 0, s[30:31]
	s_barrier
	ds_read_b128 v[170:173], v164 offset:49152
	ds_read_b128 v[174:177], v164 offset:50176
	ds_read_b128 v[178:181], v164 offset:51200
	ds_read_b128 v[182:185], v164 offset:52224
	ds_read_b128 v[186:189], v164 offset:53248
	ds_read_b128 v[190:193], v164 offset:54272
	ds_read_b128 v[194:197], v164 offset:55296
	ds_read_b128 v[198:201], v164 offset:56320
	global_load_lds_dwordx4 v[220:221], off
	v_lshl_add_u64 v[220:221], v[222:223], 0, s[30:31]
	s_mov_b32 m0, s78
	s_nop 0
	global_load_lds_dwordx4 v[220:221], off
	s_barrier
	s_waitcnt lgkmcnt(0)
	s_setprio 1
	s_waitcnt lgkmcnt(0)
	v_mfma_f32_16x16x32_bf16 v[60:63], v[148:151], v[170:173], v[60:63]
	v_mfma_f32_16x16x32_bf16 v[56:59], v[158:161], v[170:173], v[56:59]
	v_mfma_f32_16x16x32_bf16 v[44:47], v[148:151], v[178:181], v[44:47]
	v_mfma_f32_16x16x32_bf16 v[40:43], v[158:161], v[178:181], v[40:43]
	v_mfma_f32_16x16x32_bf16 v[28:31], v[148:151], v[186:189], v[28:31]
	v_mfma_f32_16x16x32_bf16 v[24:27], v[158:161], v[186:189], v[24:27]
	v_mfma_f32_16x16x32_bf16 v[12:15], v[148:151], v[194:197], v[12:15]
	v_mfma_f32_16x16x32_bf16 v[8:11], v[158:161], v[194:197], v[8:11]
	v_mfma_f32_16x16x32_bf16 v[60:63], v[152:155], v[174:177], v[60:63]
	v_mfma_f32_16x16x32_bf16 v[56:59], v[166:169], v[174:177], v[56:59]
	v_mfma_f32_16x16x32_bf16 v[44:47], v[152:155], v[182:185], v[44:47]
	v_mfma_f32_16x16x32_bf16 v[40:43], v[166:169], v[182:185], v[40:43]
	v_mfma_f32_16x16x32_bf16 v[28:31], v[152:155], v[190:193], v[28:31]
	v_mfma_f32_16x16x32_bf16 v[24:27], v[166:169], v[190:193], v[24:27]
	v_mfma_f32_16x16x32_bf16 v[12:15], v[152:155], v[198:201], v[12:15]
	v_mfma_f32_16x16x32_bf16 v[8:11], v[166:169], v[198:201], v[8:11]
	s_setprio 0
	s_barrier
	s_add_i32 s10, s11, s66
	v_lshl_add_u64 v[148:149], v[218:219], 0, s[34:35]
	s_mov_b32 m0, s10
	s_nop 0
	global_load_lds_dwordx4 v[148:149], off
	v_lshl_add_u64 v[148:149], v[218:219], 0, s[38:39]
	s_add_i32 m0, s10, 0x2000
	s_nop 0
	global_load_lds_dwordx4 v[148:149], off
	s_waitcnt vmcnt(6)
	s_barrier
	s_setprio 1
	v_mfma_f32_16x16x32_bf16 v[52:55], v[202:205], v[170:173], v[52:55]
	v_mfma_f32_16x16x32_bf16 v[48:51], v[210:213], v[170:173], v[48:51]
	v_mfma_f32_16x16x32_bf16 v[36:39], v[202:205], v[178:181], v[36:39]
	v_mfma_f32_16x16x32_bf16 v[32:35], v[210:213], v[178:181], v[32:35]
	v_mfma_f32_16x16x32_bf16 v[20:23], v[202:205], v[186:189], v[20:23]
	v_mfma_f32_16x16x32_bf16 v[16:19], v[210:213], v[186:189], v[16:19]
	v_mfma_f32_16x16x32_bf16 v[4:7], v[202:205], v[194:197], v[4:7]
	v_mfma_f32_16x16x32_bf16 v[0:3], v[210:213], v[194:197], v[0:3]
	v_mfma_f32_16x16x32_bf16 v[52:55], v[206:209], v[174:177], v[52:55]
	v_mfma_f32_16x16x32_bf16 v[48:51], v[214:217], v[174:177], v[48:51]
	v_mfma_f32_16x16x32_bf16 v[36:39], v[206:209], v[182:185], v[36:39]
	v_mfma_f32_16x16x32_bf16 v[32:35], v[214:217], v[182:185], v[32:35]
	v_mfma_f32_16x16x32_bf16 v[20:23], v[206:209], v[190:193], v[20:23]
	v_mfma_f32_16x16x32_bf16 v[16:19], v[214:217], v[190:193], v[16:19]
	v_mfma_f32_16x16x32_bf16 v[4:7], v[206:209], v[198:201], v[4:7]
	v_mfma_f32_16x16x32_bf16 v[0:3], v[214:217], v[198:201], v[0:3]
	s_setprio 0
	s_add_i32 s57, s57, 2
	s_add_u32 s55, s55, 0x8000
	s_addc_u32 s56, s56, 0
	s_add_u32 s8, s8, 0x100
	s_addc_u32 s9, s9, 0
	s_cmp_gt_u32 s57, 29
	s_barrier
	s_cbranch_scc0 .LBB0_316
	s_lshl_b32 s95, s6, 8
	s_and_b32 s8, s52, 0xff
	s_add_i32 s95, s95, s79
	s_and_b32 s6, s52, 0xf8
	s_cmp_eq_u32 s6, 16
	s_cselect_b64 s[56:57], -1, 0
	v_and_b32_e32 v188, 4, v136
	v_mul_u32_u24_e32 v188, 6, v188
	v_mov_b32_e32 v189, 0
	s_mov_b64 s[98:99], -1
	s_cmp_lg_u32 s6, 16
	s_cbranch_scc1 .Lproj_keep
	s_cmpk_ge_u32 s95, 0x4000
	s_cbranch_scc1 .Lproj_keep
	s_mov_b64 s[98:99], 0
.Lproj_keep:
	s_cmp_gt_u32 s8, 19
	s_cselect_b64 s[52:53], -1, 0
	s_and_b64 s[6:7], s[52:53], exec
	s_cselect_b32 s94, s84, 0x2cc0000
	s_cselect_b32 s93, s85, 0x24c0000
	s_lshl_b32 s45, s8, 8
	s_cmp_eq_u32 s8, 24
	s_cselect_b64 s[50:51], -1, 0
	s_and_b64 s[6:7], s[52:53], exec
	s_cselect_b32 s54, s86, 0xfffff000
	s_ashr_i32 s6, s95, 1
	v_or_b32_e32 v150, s95, v137
	s_and_b32 s97, s6, 0xfffff800
	s_ashr_i32 s6, s95, 9
	v_cndmask_b32_e64 v134, 0, 1, s[56:57]
	v_or_b32_e32 v148, s45, v136
	s_addk_i32 s97, 0xf800
	s_and_b32 s96, s6, -8
	v_cmp_gt_i32_e32 vcc, s87, v150
	v_cmp_ne_u32_e64 s[6:7], 1, v134
	s_and_saveexec_b64 s[58:59], vcc
	s_cbranch_execz .LBB0_348
	v_ashrrev_i32_e32 v151, 31, v150
	v_lshl_add_u64 v[152:153], v[150:151], 2, s[22:23]
	global_load_dword v152, v[152:153], off
	s_and_b64 vcc, exec, s[6:7]
	v_mov_b64_e32 v[154:155], 0
	s_cbranch_vccnz .LBB0_324
	v_cmp_lt_i32_e32 vcc, s88, v150
	s_and_saveexec_b64 s[8:9], vcc
	s_xor_b64 s[8:9], exec, s[8:9]
	v_lshlrev_b32_e32 v134, 9, v150
	s_lshl_b32 s55, s94, 2
	v_and_b32_e32 v134, 0x7fff9800, v134
	s_add_u32 s60, s18, s55
	v_add_u32_e32 v134, v134, v162
	s_addc_u32 s61, s19, 0
	v_lshlrev_b64 v[154:155], 12, v[134:135]
	v_lshl_add_u64 v[154:155], s[60:61], 0, v[154:155]
	s_andn2_saveexec_b64 s[8:9], s[8:9]
	s_cbranch_execz .LBB0_323
	v_and_b32_e32 v134, 0xfcf, v150
	v_add_u32_e32 v154, s97, v134
	s_lshl_b32 s55, s93, 2
	v_ashrrev_i32_e32 v155, 31, v154
	s_add_u32 s60, s18, s55
	v_lshlrev_b64 v[154:155], 12, v[154:155]
	s_addc_u32 s61, s19, 0
	v_lshl_add_u64 v[154:155], s[60:61], 0, v[154:155]
	v_cmp_lt_u32_e32 vcc, s89, v134
	s_nop 1
	v_cndmask_b32_e32 v155, 0, v155, vcc
	v_cndmask_b32_e32 v154, 0, v154, vcc

.LBB0_324:
	v_mov_b64_e32 v[160:161], s[20:21]
	s_waitcnt vmcnt(0)
	v_pk_mul_f32 v[126:127], v[126:127], v[152:153] op_sel_hi:[1,0]
	v_pk_mul_f32 v[124:125], v[124:125], v[152:153] op_sel_hi:[1,0]
	v_mad_i64_i32 v[160:161], s[60:61], v150, s90, v[160:161]
	v_lshlrev_b32_e32 v134, 1, v148
	v_cmp_ne_u64_e64 s[8:9], 0, v[154:155]
	v_cvt_pk_bf16_f32 v158, v124, v125
	v_cvt_pk_bf16_f32 v159, v126, v127
	v_lshl_add_u64 v[160:161], v[160:161], 0, v[134:135]
	v_mov_b32_e32 v182, v158
	v_mov_b32_e32 v183, v159
	s_and_saveexec_b64 s[60:61], s[8:9]
	s_cbranch_execz .LBB0_326
	v_add_u32_e32 v166, s54, v148
	v_ashrrev_i32_e32 v167, 31, v166
	v_lshl_add_u64 v[166:167], v[166:167], 2, v[154:155]
	global_store_dwordx4 v[166:167], v[124:127], off
.LBB0_326:
	s_or_b64 exec, exec, s[60:61]
	v_lshlrev_b32_e32 v134, 7, v150
	v_cmp_gt_i32_e32 vcc, s72, v150
	v_and_b32_e32 v134, 0x7e780, v134
	s_and_b64 s[60:61], s[56:57], vcc
	v_lshlrev_b32_e32 v134, 1, v134
	s_and_saveexec_b64 s[62:63], s[60:61]
	s_cbranch_execz .LBB0_328
	s_add_i32 s55, s54, s45
	s_and_b64 vcc, s[52:53], exec
	s_cselect_b32 s33, s76, s74
	s_cselect_b32 s10, s75, s73
	s_ashr_i32 s11, s55, 7
	s_add_i32 vcc_lo, s11, s96
	s_ashr_i32 vcc_hi, vcc_lo, 31
	s_lshl_b64 vcc, vcc, 20
	s_add_u32 vcc_lo, s10, vcc_lo
	s_addc_u32 vcc_hi, s33, vcc_hi
	v_lshl_add_u64 v[166:167], vcc, 0, v[134:135]
	v_lshlrev_b32_e32 v168, 1, v136
	v_mov_b32_e32 v169, v135
	v_lshl_add_u64 v[166:167], v[166:167], 0, v[168:169]
	v_mov_b32_e32 v194, v166
	v_mov_b32_e32 v195, v167

.LBB0_330:
	s_or_b64 exec, exec, s[62:63]
	v_mov_b32_e32 v153, v152
	v_mov_b32_e32 v124, v152
	v_mov_b32_e32 v125, v152
	v_pk_mul_f32 v[122:123], v[122:123], v[124:125]
	v_pk_mul_f32 v[120:121], v[120:121], v[152:153]
	v_cvt_pk_bf16_f32 v125, v122, v123
	v_cvt_pk_bf16_f32 v124, v120, v121
	v_mov_b32_e32 v184, v124
	v_mov_b32_e32 v185, v125
	s_nop 1
	v_permlane16_swap_b32_e32 v182, v184
	v_permlane16_swap_b32_e32 v183, v185
	s_mov_b64 exec, s[98:99]
	v_lshl_add_u64 v[186:187], v[160:161], 0, v[188:189]
	global_store_dwordx4 v[186:187], v[182:185], off
	s_mov_b64 exec, -1
	s_and_saveexec_b64 s[62:63], s[8:9]
	s_cbranch_execz .LBB0_332
	s_ashr_i32 s55, s54, 31
	v_mov_b32_e32 v149, v135
	v_lshl_add_u64 v[126:127], v[148:149], 0, s[54:55]
	v_lshl_add_u64 v[126:127], v[126:127], 2, v[154:155]
	global_store_dwordx4 v[126:127], v[120:123], off offset:64
.LBB0_332:
	s_or_b64 exec, exec, s[62:63]
	v_or_b32_e32 v126, 16, v148
	s_and_saveexec_b64 s[62:63], s[60:61]
	s_cbranch_execz .LBB0_334
	s_add_i32 s10, s54, s45
	s_and_b64 vcc, s[52:53], exec
	s_cselect_b32 s11, s76, s74
	s_cselect_b32 s33, s75, s73
	s_ashr_i32 s10, s10, 7
	s_add_i32 vcc_lo, s10, s96
	s_ashr_i32 vcc_hi, vcc_lo, 31
	s_lshl_b64 vcc, vcc, 20
	s_add_u32 vcc_lo, s33, vcc_lo
	s_addc_u32 vcc_hi, s11, vcc_hi
	v_and_b32_e32 v127, 0x7c, v126
	v_lshl_add_u64 v[166:167], vcc, 0, v[134:135]
	v_lshlrev_b32_e32 v168, 1, v127
	v_mov_b32_e32 v169, v135
	v_lshl_add_u64 v[166:167], v[166:167], 0, v[168:169]
	v_lshl_add_u64 v[196:197], v[194:195], 0, v[188:189]
	global_store_dwordx4 v[196:197], v[182:185], off

.LBB0_336:
	s_or_b64 exec, exec, s[62:63]
	s_nop 0
	v_mov_b32_e32 v120, v152
	v_mov_b32_e32 v121, v152
	v_pk_mul_f32 v[118:119], v[118:119], v[120:121]
	v_pk_mul_f32 v[116:117], v[116:117], v[152:153]
	v_cvt_pk_bf16_f32 v121, v118, v119
	v_cvt_pk_bf16_f32 v120, v116, v117
	v_mov_b32_e32 v182, v120
	v_mov_b32_e32 v183, v121
	s_and_saveexec_b64 s[62:63], s[8:9]
	s_cbranch_execz .LBB0_338
	s_ashr_i32 s55, s54, 31
	v_mov_b32_e32 v149, v135
	v_lshl_add_u64 v[122:123], v[148:149], 0, s[54:55]
	v_lshl_add_u64 v[122:123], v[122:123], 2, v[154:155]
	global_store_dwordx4 v[122:123], v[116:119], off offset:512
.LBB0_338:
	s_or_b64 exec, exec, s[62:63]
	v_or_b32_e32 v122, 0x80, v148
	s_and_saveexec_b64 s[62:63], s[60:61]
	s_cbranch_execz .LBB0_340
	v_add_u32_e32 v123, s54, v122
	v_ashrrev_i32_e32 v123, 7, v123
	v_add_u32_e32 v124, s96, v123
	s_and_b64 vcc, s[52:53], exec
	v_ashrrev_i32_e32 v125, 31, v124
	s_cselect_b32 vcc_hi, s76, s74
	s_cselect_b32 vcc_lo, s75, s73
	v_lshlrev_b64 v[124:125], 20, v[124:125]
	v_lshl_add_u64 v[124:125], vcc, 0, v[124:125]
	v_lshl_add_u64 v[124:125], v[124:125], 0, v[134:135]
	v_lshlrev_b32_e32 v126, 1, v136
	v_mov_b32_e32 v127, v135
	v_lshl_add_u64 v[124:125], v[124:125], 0, v[126:127]
	v_mov_b32_e32 v194, v124
	v_mov_b32_e32 v195, v125

.LBB0_342:
	s_or_b64 exec, exec, s[62:63]
	s_nop 0
	v_mov_b32_e32 v116, v152
	v_mov_b32_e32 v117, v152
	v_pk_mul_f32 v[114:115], v[114:115], v[116:117]
	v_pk_mul_f32 v[112:113], v[112:113], v[152:153]
	v_cvt_pk_bf16_f32 v117, v114, v115
	v_cvt_pk_bf16_f32 v116, v112, v113
	v_mov_b32_e32 v184, v116
	v_mov_b32_e32 v185, v117
	s_nop 1
	v_permlane16_swap_b32_e32 v182, v184
	v_permlane16_swap_b32_e32 v183, v185
	s_mov_b64 exec, s[98:99]
	v_lshl_add_u64 v[186:187], v[160:161], 0, v[188:189]
	global_store_dwordx4 v[186:187], v[182:185], off offset:256
	s_mov_b64 exec, -1
	s_and_saveexec_b64 s[62:63], s[8:9]
	s_cbranch_execz .LBB0_344
	s_ashr_i32 s55, s54, 31
	v_mov_b32_e32 v149, v135
	v_lshl_add_u64 v[118:119], v[148:149], 0, s[54:55]
	v_lshl_add_u64 v[118:119], v[118:119], 2, v[154:155]
	global_store_dwordx4 v[118:119], v[112:115], off offset:576
.LBB0_344:
	s_or_b64 exec, exec, s[62:63]
	v_or_b32_e32 v118, 0x90, v148
	s_and_saveexec_b64 s[8:9], s[60:61]
	s_cbranch_execz .LBB0_346
	v_add_u32_e32 v119, s54, v118
	v_ashrrev_i32_e32 v119, 7, v119
	v_add_u32_e32 v120, s96, v119
	s_and_b64 s[60:61], s[52:53], exec
	v_ashrrev_i32_e32 v121, 31, v120
	s_cselect_b32 s61, s76, s74
	s_cselect_b32 s60, s75, s73
	v_lshlrev_b64 v[120:121], 20, v[120:121]
	v_lshl_add_u64 v[120:121], s[60:61], 0, v[120:121]
	v_and_b32_e32 v119, 0x7c, v118
	v_lshl_add_u64 v[120:121], v[120:121], 0, v[134:135]
	v_lshlrev_b32_e32 v134, 1, v119
	v_lshl_add_u64 v[120:121], v[120:121], 0, v[134:135]
	v_lshl_add_u64 v[196:197], v[194:195], 0, v[188:189]
	global_store_dwordx4 v[196:197], v[182:185], off

.LBB0_355:
	v_mov_b64_e32 v[118:119], s[20:21]
	s_waitcnt vmcnt(0)
	v_pk_mul_f32 v[110:111], v[110:111], v[112:113] op_sel_hi:[1,0]
	v_pk_mul_f32 v[108:109], v[108:109], v[112:113] op_sel_hi:[1,0]
	v_mad_i64_i32 v[118:119], s[60:61], v116, s90, v[118:119]
	v_lshlrev_b32_e32 v134, 1, v148
	v_cmp_ne_u64_e64 s[8:9], 0, v[114:115]
	v_cvt_pk_bf16_f32 v120, v108, v109
	v_cvt_pk_bf16_f32 v121, v110, v111
	v_lshl_add_u64 v[118:119], v[118:119], 0, v[134:135]
	v_mov_b32_e32 v182, v120
	v_mov_b32_e32 v183, v121
	s_and_saveexec_b64 s[60:61], s[8:9]
	s_cbranch_execz .LBB0_357
	v_add_u32_e32 v122, s54, v148
	v_ashrrev_i32_e32 v123, 31, v122
	v_lshl_add_u64 v[122:123], v[122:123], 2, v[114:115]
	global_store_dwordx4 v[122:123], v[108:111], off
.LBB0_357:
	s_or_b64 exec, exec, s[60:61]
	v_lshlrev_b32_e32 v113, 7, v116
	v_cmp_gt_i32_e32 vcc, s72, v116
	v_and_b32_e32 v113, 0x7ef80, v113
	s_and_b64 s[60:61], s[56:57], vcc
	v_lshlrev_b32_e32 v134, 1, v113
	s_and_saveexec_b64 s[62:63], s[60:61]
	s_cbranch_execz .LBB0_359
	s_add_i32 s10, s54, s45
	s_and_b64 vcc, s[52:53], exec
	s_cselect_b32 s11, s76, s74
	s_cselect_b32 s33, s75, s73
	s_ashr_i32 s10, s10, 7
	s_add_i32 vcc_lo, s10, s96
	s_ashr_i32 vcc_hi, vcc_lo, 31
	s_lshl_b64 vcc, vcc, 20
	s_add_u32 vcc_lo, s33, vcc_lo
	s_addc_u32 vcc_hi, s11, vcc_hi
	v_lshl_add_u64 v[122:123], vcc, 0, v[134:135]
	v_lshlrev_b32_e32 v124, 1, v136
	v_mov_b32_e32 v125, v135
	v_lshl_add_u64 v[122:123], v[122:123], 0, v[124:125]
	v_mov_b32_e32 v194, v122
	v_mov_b32_e32 v195, v123

.LBB0_361:
	s_or_b64 exec, exec, s[62:63]
	v_mov_b32_e32 v113, v112
	v_mov_b32_e32 v108, v112
	v_mov_b32_e32 v109, v112
	v_pk_mul_f32 v[106:107], v[106:107], v[108:109]
	v_pk_mul_f32 v[104:105], v[104:105], v[112:113]
	v_cvt_pk_bf16_f32 v109, v106, v107
	v_cvt_pk_bf16_f32 v108, v104, v105
	v_mov_b32_e32 v184, v108
	v_mov_b32_e32 v185, v109
	s_nop 1
	v_permlane16_swap_b32_e32 v182, v184
	v_permlane16_swap_b32_e32 v183, v185
	s_mov_b64 exec, s[98:99]
	v_lshl_add_u64 v[186:187], v[118:119], 0, v[188:189]
	global_store_dwordx4 v[186:187], v[182:185], off
	s_mov_b64 exec, -1
	s_and_saveexec_b64 s[62:63], s[8:9]
	s_cbranch_execz .LBB0_363
	s_ashr_i32 s55, s54, 31
	v_mov_b32_e32 v149, v135
	v_lshl_add_u64 v[110:111], v[148:149], 0, s[54:55]
	v_lshl_add_u64 v[110:111], v[110:111], 2, v[114:115]
	global_store_dwordx4 v[110:111], v[104:107], off offset:64
.LBB0_363:
	s_or_b64 exec, exec, s[62:63]
	v_or_b32_e32 v110, 16, v148
	s_and_saveexec_b64 s[62:63], s[60:61]
	s_cbranch_execz .LBB0_365
	s_add_i32 s10, s54, s45
	s_and_b64 vcc, s[52:53], exec
	s_cselect_b32 s11, s76, s74
	s_cselect_b32 s33, s75, s73
	s_ashr_i32 s10, s10, 7
	s_add_i32 vcc_lo, s10, s96
	s_ashr_i32 vcc_hi, vcc_lo, 31
	s_lshl_b64 vcc, vcc, 20
	s_add_u32 vcc_lo, s33, vcc_lo
	s_addc_u32 vcc_hi, s11, vcc_hi
	v_and_b32_e32 v111, 0x7c, v110
	v_lshl_add_u64 v[120:121], vcc, 0, v[134:135]
	v_lshlrev_b32_e32 v122, 1, v111
	v_mov_b32_e32 v123, v135
	v_lshl_add_u64 v[120:121], v[120:121], 0, v[122:123]
	v_lshl_add_u64 v[196:197], v[194:195], 0, v[188:189]
	global_store_dwordx4 v[196:197], v[182:185], off

.LBB0_367:
	s_or_b64 exec, exec, s[62:63]
	s_nop 0
	v_mov_b32_e32 v104, v112
	v_mov_b32_e32 v105, v112
	v_pk_mul_f32 v[102:103], v[102:103], v[104:105]
	v_pk_mul_f32 v[100:101], v[100:101], v[112:113]
	v_cvt_pk_bf16_f32 v105, v102, v103
	v_cvt_pk_bf16_f32 v104, v100, v101
	v_mov_b32_e32 v182, v104
	v_mov_b32_e32 v183, v105
	s_and_saveexec_b64 s[62:63], s[8:9]
	s_cbranch_execz .LBB0_369
	s_ashr_i32 s55, s54, 31
	v_mov_b32_e32 v149, v135
	v_lshl_add_u64 v[106:107], v[148:149], 0, s[54:55]
	v_lshl_add_u64 v[106:107], v[106:107], 2, v[114:115]
	global_store_dwordx4 v[106:107], v[100:103], off offset:512
.LBB0_369:
	s_or_b64 exec, exec, s[62:63]
	v_or_b32_e32 v106, 0x80, v148
	s_and_saveexec_b64 s[62:63], s[60:61]
	s_cbranch_execz .LBB0_371
	v_add_u32_e32 v107, s54, v106
	v_ashrrev_i32_e32 v107, 7, v107
	v_add_u32_e32 v108, s96, v107
	s_and_b64 vcc, s[52:53], exec
	v_ashrrev_i32_e32 v109, 31, v108
	s_cselect_b32 vcc_hi, s76, s74
	s_cselect_b32 vcc_lo, s75, s73
	v_lshlrev_b64 v[108:109], 20, v[108:109]
	v_lshl_add_u64 v[108:109], vcc, 0, v[108:109]
	v_lshl_add_u64 v[108:109], v[108:109], 0, v[134:135]
	v_lshlrev_b32_e32 v110, 1, v136
	v_mov_b32_e32 v111, v135
	v_lshl_add_u64 v[108:109], v[108:109], 0, v[110:111]
	v_mov_b32_e32 v194, v108
	v_mov_b32_e32 v195, v109

.LBB0_373:
	s_or_b64 exec, exec, s[62:63]
	s_nop 0
	v_mov_b32_e32 v100, v112
	v_mov_b32_e32 v101, v112
	v_pk_mul_f32 v[98:99], v[98:99], v[100:101]
	v_pk_mul_f32 v[96:97], v[96:97], v[112:113]
	v_cvt_pk_bf16_f32 v101, v98, v99
	v_cvt_pk_bf16_f32 v100, v96, v97
	v_mov_b32_e32 v184, v100
	v_mov_b32_e32 v185, v101
	s_nop 1
	v_permlane16_swap_b32_e32 v182, v184
	v_permlane16_swap_b32_e32 v183, v185
	s_mov_b64 exec, s[98:99]
	v_lshl_add_u64 v[186:187], v[118:119], 0, v[188:189]
	global_store_dwordx4 v[186:187], v[182:185], off offset:256
	s_mov_b64 exec, -1
	s_and_saveexec_b64 s[62:63], s[8:9]
	s_cbranch_execz .LBB0_375
	s_ashr_i32 s55, s54, 31
	v_mov_b32_e32 v149, v135
	v_lshl_add_u64 v[102:103], v[148:149], 0, s[54:55]
	v_lshl_add_u64 v[102:103], v[102:103], 2, v[114:115]
	global_store_dwordx4 v[102:103], v[96:99], off offset:576
.LBB0_375:
	s_or_b64 exec, exec, s[62:63]
	v_or_b32_e32 v102, 0x90, v148
	s_and_saveexec_b64 s[8:9], s[60:61]
	s_cbranch_execz .LBB0_377
	v_add_u32_e32 v103, s54, v102
	v_ashrrev_i32_e32 v103, 7, v103
	v_add_u32_e32 v104, s96, v103
	s_and_b64 s[60:61], s[52:53], exec
	v_ashrrev_i32_e32 v105, 31, v104
	s_cselect_b32 s61, s76, s74
	s_cselect_b32 s60, s75, s73
	v_lshlrev_b64 v[104:105], 20, v[104:105]
	v_lshl_add_u64 v[104:105], s[60:61], 0, v[104:105]
	v_and_b32_e32 v103, 0x7c, v102
	v_lshl_add_u64 v[104:105], v[104:105], 0, v[134:135]
	v_lshlrev_b32_e32 v134, 1, v103
	v_lshl_add_u64 v[104:105], v[104:105], 0, v[134:135]
	v_lshl_add_u64 v[196:197], v[194:195], 0, v[188:189]
	global_store_dwordx4 v[196:197], v[182:185], off

.LBB0_386:
	v_mov_b64_e32 v[102:103], s[20:21]
	s_waitcnt vmcnt(0)
	v_pk_mul_f32 v[94:95], v[94:95], v[96:97] op_sel_hi:[1,0]
	v_pk_mul_f32 v[92:93], v[92:93], v[96:97] op_sel_hi:[1,0]
	v_mad_i64_i32 v[102:103], s[60:61], v100, s90, v[102:103]
	v_lshlrev_b32_e32 v134, 1, v148
	v_cmp_ne_u64_e64 s[8:9], 0, v[98:99]
	v_cvt_pk_bf16_f32 v104, v92, v93
	v_cvt_pk_bf16_f32 v105, v94, v95
	v_lshl_add_u64 v[102:103], v[102:103], 0, v[134:135]
	v_mov_b32_e32 v182, v104
	v_mov_b32_e32 v183, v105
	s_and_saveexec_b64 s[60:61], s[8:9]
	s_cbranch_execz .LBB0_388
	v_add_u32_e32 v106, s54, v148
	v_ashrrev_i32_e32 v107, 31, v106
	v_lshl_add_u64 v[106:107], v[106:107], 2, v[98:99]
	global_store_dwordx4 v[106:107], v[92:95], off
.LBB0_388:
	s_or_b64 exec, exec, s[60:61]
	v_lshlrev_b32_e32 v97, 7, v100
	v_cmp_gt_i32_e32 vcc, s72, v100
	v_and_b32_e32 v97, 0x7f780, v97
	s_and_b64 s[60:61], s[56:57], vcc
	v_lshlrev_b32_e32 v134, 1, v97
	s_and_saveexec_b64 s[62:63], s[60:61]
	s_cbranch_execz .LBB0_390
	s_add_i32 s10, s54, s45
	s_and_b64 vcc, s[52:53], exec
	s_cselect_b32 s11, s76, s74
	s_cselect_b32 s33, s75, s73
	s_ashr_i32 s10, s10, 7
	s_add_i32 vcc_lo, s10, s96
	s_ashr_i32 vcc_hi, vcc_lo, 31
	s_lshl_b64 vcc, vcc, 20
	s_add_u32 vcc_lo, s33, vcc_lo
	s_addc_u32 vcc_hi, s11, vcc_hi
	v_lshl_add_u64 v[106:107], vcc, 0, v[134:135]
	v_lshlrev_b32_e32 v108, 1, v136
	v_mov_b32_e32 v109, v135
	v_lshl_add_u64 v[106:107], v[106:107], 0, v[108:109]
	v_mov_b32_e32 v194, v106
	v_mov_b32_e32 v195, v107

.LBB0_392:
	s_or_b64 exec, exec, s[62:63]
	v_mov_b32_e32 v97, v96
	v_mov_b32_e32 v92, v96
	v_mov_b32_e32 v93, v96
	v_pk_mul_f32 v[90:91], v[90:91], v[92:93]
	v_pk_mul_f32 v[88:89], v[88:89], v[96:97]
	v_cvt_pk_bf16_f32 v93, v90, v91
	v_cvt_pk_bf16_f32 v92, v88, v89
	v_mov_b32_e32 v184, v92
	v_mov_b32_e32 v185, v93
	s_nop 1
	v_permlane16_swap_b32_e32 v182, v184
	v_permlane16_swap_b32_e32 v183, v185
	s_mov_b64 exec, s[98:99]
	v_lshl_add_u64 v[186:187], v[102:103], 0, v[188:189]
	global_store_dwordx4 v[186:187], v[182:185], off
	s_mov_b64 exec, -1
	s_and_saveexec_b64 s[62:63], s[8:9]
	s_cbranch_execz .LBB0_394
	s_ashr_i32 s55, s54, 31
	v_mov_b32_e32 v149, v135
	v_lshl_add_u64 v[94:95], v[148:149], 0, s[54:55]
	v_lshl_add_u64 v[94:95], v[94:95], 2, v[98:99]
	global_store_dwordx4 v[94:95], v[88:91], off offset:64
.LBB0_394:
	s_or_b64 exec, exec, s[62:63]
	v_or_b32_e32 v94, 16, v148
	s_and_saveexec_b64 s[62:63], s[60:61]
	s_cbranch_execz .LBB0_396
	s_add_i32 s10, s54, s45
	s_and_b64 vcc, s[52:53], exec
	s_cselect_b32 s11, s76, s74
	s_cselect_b32 s33, s75, s73
	s_ashr_i32 s10, s10, 7
	s_add_i32 vcc_lo, s10, s96
	s_ashr_i32 vcc_hi, vcc_lo, 31
	s_lshl_b64 vcc, vcc, 20
	s_add_u32 vcc_lo, s33, vcc_lo
	s_addc_u32 vcc_hi, s11, vcc_hi
	v_and_b32_e32 v95, 0x7c, v94
	v_lshl_add_u64 v[104:105], vcc, 0, v[134:135]
	v_lshlrev_b32_e32 v106, 1, v95
	v_mov_b32_e32 v107, v135
	v_lshl_add_u64 v[104:105], v[104:105], 0, v[106:107]
	v_lshl_add_u64 v[196:197], v[194:195], 0, v[188:189]
	global_store_dwordx4 v[196:197], v[182:185], off

.LBB0_398:
	s_or_b64 exec, exec, s[62:63]
	s_nop 0
	v_mov_b32_e32 v88, v96
	v_mov_b32_e32 v89, v96
	v_pk_mul_f32 v[86:87], v[86:87], v[88:89]
	v_pk_mul_f32 v[84:85], v[84:85], v[96:97]
	v_cvt_pk_bf16_f32 v89, v86, v87
	v_cvt_pk_bf16_f32 v88, v84, v85
	v_mov_b32_e32 v182, v88
	v_mov_b32_e32 v183, v89
	s_and_saveexec_b64 s[62:63], s[8:9]
	s_cbranch_execz .LBB0_400
	s_ashr_i32 s55, s54, 31
	v_mov_b32_e32 v149, v135
	v_lshl_add_u64 v[90:91], v[148:149], 0, s[54:55]
	v_lshl_add_u64 v[90:91], v[90:91], 2, v[98:99]
	global_store_dwordx4 v[90:91], v[84:87], off offset:512
.LBB0_400:
	s_or_b64 exec, exec, s[62:63]
	v_or_b32_e32 v90, 0x80, v148
	s_and_saveexec_b64 s[62:63], s[60:61]
	s_cbranch_execz .LBB0_402
	v_add_u32_e32 v91, s54, v90
	v_ashrrev_i32_e32 v91, 7, v91
	v_add_u32_e32 v92, s96, v91
	s_and_b64 vcc, s[52:53], exec
	v_ashrrev_i32_e32 v93, 31, v92
	s_cselect_b32 vcc_hi, s76, s74
	s_cselect_b32 vcc_lo, s75, s73
	v_lshlrev_b64 v[92:93], 20, v[92:93]
	v_lshl_add_u64 v[92:93], vcc, 0, v[92:93]
	v_lshl_add_u64 v[92:93], v[92:93], 0, v[134:135]
	v_lshlrev_b32_e32 v94, 1, v136
	v_mov_b32_e32 v95, v135
	v_lshl_add_u64 v[92:93], v[92:93], 0, v[94:95]
	v_mov_b32_e32 v194, v92
	v_mov_b32_e32 v195, v93

.LBB0_404:
	s_or_b64 exec, exec, s[62:63]
	s_nop 0
	v_mov_b32_e32 v84, v96
	v_mov_b32_e32 v85, v96
	v_pk_mul_f32 v[82:83], v[82:83], v[84:85]
	v_pk_mul_f32 v[80:81], v[80:81], v[96:97]
	v_cvt_pk_bf16_f32 v85, v82, v83
	v_cvt_pk_bf16_f32 v84, v80, v81
	v_mov_b32_e32 v184, v84
	v_mov_b32_e32 v185, v85
	s_nop 1
	v_permlane16_swap_b32_e32 v182, v184
	v_permlane16_swap_b32_e32 v183, v185
	s_mov_b64 exec, s[98:99]
	v_lshl_add_u64 v[186:187], v[102:103], 0, v[188:189]
	global_store_dwordx4 v[186:187], v[182:185], off offset:256
	s_mov_b64 exec, -1
	s_and_saveexec_b64 s[62:63], s[8:9]
	s_cbranch_execz .LBB0_406
	s_ashr_i32 s55, s54, 31
	v_mov_b32_e32 v149, v135
	v_lshl_add_u64 v[86:87], v[148:149], 0, s[54:55]
	v_lshl_add_u64 v[86:87], v[86:87], 2, v[98:99]
	global_store_dwordx4 v[86:87], v[80:83], off offset:576
.LBB0_406:
	s_or_b64 exec, exec, s[62:63]
	v_or_b32_e32 v86, 0x90, v148
	s_and_saveexec_b64 s[8:9], s[60:61]
	s_cbranch_execz .LBB0_408
	v_add_u32_e32 v87, s54, v86
	v_ashrrev_i32_e32 v87, 7, v87
	v_add_u32_e32 v88, s96, v87
	s_and_b64 s[60:61], s[52:53], exec
	v_ashrrev_i32_e32 v89, 31, v88
	s_cselect_b32 s61, s76, s74
	s_cselect_b32 s60, s75, s73
	v_lshlrev_b64 v[88:89], 20, v[88:89]
	v_lshl_add_u64 v[88:89], s[60:61], 0, v[88:89]
	v_and_b32_e32 v87, 0x7c, v86
	v_lshl_add_u64 v[88:89], v[88:89], 0, v[134:135]
	v_lshlrev_b32_e32 v134, 1, v87
	v_lshl_add_u64 v[88:89], v[88:89], 0, v[134:135]
	v_lshl_add_u64 v[196:197], v[194:195], 0, v[188:189]
	global_store_dwordx4 v[196:197], v[182:185], off

.LBB0_417:
	v_mov_b64_e32 v[86:87], s[20:21]
	s_waitcnt vmcnt(0)
	v_pk_mul_f32 v[78:79], v[78:79], v[80:81] op_sel_hi:[1,0]
	v_pk_mul_f32 v[76:77], v[76:77], v[80:81] op_sel_hi:[1,0]
	v_mad_i64_i32 v[86:87], s[60:61], v84, s90, v[86:87]
	v_lshlrev_b32_e32 v134, 1, v148
	v_cmp_ne_u64_e64 s[8:9], 0, v[82:83]
	v_cvt_pk_bf16_f32 v88, v76, v77
	v_cvt_pk_bf16_f32 v89, v78, v79
	v_lshl_add_u64 v[86:87], v[86:87], 0, v[134:135]
	v_mov_b32_e32 v182, v88
	v_mov_b32_e32 v183, v89
	s_and_saveexec_b64 s[60:61], s[8:9]
	s_cbranch_execz .LBB0_419
	v_add_u32_e32 v90, s54, v148
	v_ashrrev_i32_e32 v91, 31, v90
	v_lshl_add_u64 v[90:91], v[90:91], 2, v[82:83]
	global_store_dwordx4 v[90:91], v[76:79], off
.LBB0_419:
	s_or_b64 exec, exec, s[60:61]
	v_lshlrev_b32_e32 v81, 7, v84
	v_cmp_gt_i32_e32 vcc, s72, v84
	v_and_b32_e32 v81, 0x7ff80, v81
	s_and_b64 s[60:61], s[56:57], vcc
	v_lshlrev_b32_e32 v134, 1, v81
	s_and_saveexec_b64 s[62:63], s[60:61]
	s_cbranch_execz .LBB0_421
	s_add_i32 s10, s54, s45
	s_and_b64 vcc, s[52:53], exec
	s_cselect_b32 s11, s76, s74
	s_cselect_b32 s33, s75, s73
	s_ashr_i32 s10, s10, 7
	s_add_i32 vcc_lo, s10, s96
	s_ashr_i32 vcc_hi, vcc_lo, 31
	s_lshl_b64 vcc, vcc, 20
	s_add_u32 vcc_lo, s33, vcc_lo
	s_addc_u32 vcc_hi, s11, vcc_hi
	v_lshl_add_u64 v[90:91], vcc, 0, v[134:135]
	v_lshlrev_b32_e32 v92, 1, v136
	v_mov_b32_e32 v93, v135
	v_lshl_add_u64 v[90:91], v[90:91], 0, v[92:93]
	v_mov_b32_e32 v194, v90
	v_mov_b32_e32 v195, v91

.LBB0_423:
	s_or_b64 exec, exec, s[62:63]
	v_mov_b32_e32 v81, v80
	v_mov_b32_e32 v76, v80
	v_mov_b32_e32 v77, v80
	v_pk_mul_f32 v[74:75], v[74:75], v[76:77]
	v_pk_mul_f32 v[72:73], v[72:73], v[80:81]
	v_cvt_pk_bf16_f32 v77, v74, v75
	v_cvt_pk_bf16_f32 v76, v72, v73
	v_mov_b32_e32 v184, v76
	v_mov_b32_e32 v185, v77
	s_nop 1
	v_permlane16_swap_b32_e32 v182, v184
	v_permlane16_swap_b32_e32 v183, v185
	s_mov_b64 exec, s[98:99]
	v_lshl_add_u64 v[186:187], v[86:87], 0, v[188:189]
	global_store_dwordx4 v[186:187], v[182:185], off
	s_mov_b64 exec, -1
	s_and_saveexec_b64 s[62:63], s[8:9]
	s_cbranch_execz .LBB0_425
	s_ashr_i32 s55, s54, 31
	v_mov_b32_e32 v149, v135
	v_lshl_add_u64 v[78:79], v[148:149], 0, s[54:55]
	v_lshl_add_u64 v[78:79], v[78:79], 2, v[82:83]
	global_store_dwordx4 v[78:79], v[72:75], off offset:64
.LBB0_425:
	s_or_b64 exec, exec, s[62:63]
	v_or_b32_e32 v78, 16, v148
	s_and_saveexec_b64 s[62:63], s[60:61]
	s_cbranch_execz .LBB0_427
	s_add_i32 s10, s54, s45
	s_and_b64 vcc, s[52:53], exec
	s_cselect_b32 s11, s76, s74
	s_cselect_b32 s33, s75, s73
	s_ashr_i32 s10, s10, 7
	s_add_i32 vcc_lo, s10, s96
	s_ashr_i32 vcc_hi, vcc_lo, 31
	s_lshl_b64 vcc, vcc, 20
	s_add_u32 vcc_lo, s33, vcc_lo
	s_addc_u32 vcc_hi, s11, vcc_hi
	v_and_b32_e32 v79, 0x7c, v78
	v_lshl_add_u64 v[88:89], vcc, 0, v[134:135]
	v_lshlrev_b32_e32 v90, 1, v79
	v_mov_b32_e32 v91, v135
	v_lshl_add_u64 v[88:89], v[88:89], 0, v[90:91]
	v_lshl_add_u64 v[196:197], v[194:195], 0, v[188:189]
	global_store_dwordx4 v[196:197], v[182:185], off

.LBB0_429:
	s_or_b64 exec, exec, s[62:63]
	s_nop 0
	v_mov_b32_e32 v72, v80
	v_mov_b32_e32 v73, v80
	v_pk_mul_f32 v[70:71], v[70:71], v[72:73]
	v_pk_mul_f32 v[68:69], v[68:69], v[80:81]
	v_cvt_pk_bf16_f32 v73, v70, v71
	v_cvt_pk_bf16_f32 v72, v68, v69
	v_mov_b32_e32 v182, v72
	v_mov_b32_e32 v183, v73
	s_and_saveexec_b64 s[62:63], s[8:9]
	s_cbranch_execz .LBB0_431
	s_ashr_i32 s55, s54, 31
	v_mov_b32_e32 v149, v135
	v_lshl_add_u64 v[74:75], v[148:149], 0, s[54:55]
	v_lshl_add_u64 v[74:75], v[74:75], 2, v[82:83]
	global_store_dwordx4 v[74:75], v[68:71], off offset:512
.LBB0_431:
	s_or_b64 exec, exec, s[62:63]
	v_or_b32_e32 v74, 0x80, v148
	s_and_saveexec_b64 s[62:63], s[60:61]
	s_cbranch_execz .LBB0_433
	v_add_u32_e32 v75, s54, v74
	v_ashrrev_i32_e32 v75, 7, v75
	v_add_u32_e32 v76, s96, v75
	s_and_b64 vcc, s[52:53], exec
	v_ashrrev_i32_e32 v77, 31, v76
	s_cselect_b32 vcc_hi, s76, s74
	s_cselect_b32 vcc_lo, s75, s73
	v_lshlrev_b64 v[76:77], 20, v[76:77]
	v_lshl_add_u64 v[76:77], vcc, 0, v[76:77]
	v_lshl_add_u64 v[76:77], v[76:77], 0, v[134:135]
	v_lshlrev_b32_e32 v78, 1, v136
	v_mov_b32_e32 v79, v135
	v_lshl_add_u64 v[76:77], v[76:77], 0, v[78:79]
	v_mov_b32_e32 v194, v76
	v_mov_b32_e32 v195, v77

.LBB0_435:
	s_or_b64 exec, exec, s[62:63]
	s_nop 0
	v_mov_b32_e32 v68, v80
	v_mov_b32_e32 v69, v80
	v_pk_mul_f32 v[66:67], v[66:67], v[68:69]
	v_pk_mul_f32 v[64:65], v[64:65], v[80:81]
	v_cvt_pk_bf16_f32 v69, v66, v67
	v_cvt_pk_bf16_f32 v68, v64, v65
	v_mov_b32_e32 v184, v68
	v_mov_b32_e32 v185, v69
	s_nop 1
	v_permlane16_swap_b32_e32 v182, v184
	v_permlane16_swap_b32_e32 v183, v185
	s_mov_b64 exec, s[98:99]
	v_lshl_add_u64 v[186:187], v[86:87], 0, v[188:189]
	global_store_dwordx4 v[186:187], v[182:185], off offset:256
	s_mov_b64 exec, -1
	s_and_saveexec_b64 s[62:63], s[8:9]
	s_cbranch_execz .LBB0_437
	s_ashr_i32 s55, s54, 31
	v_mov_b32_e32 v149, v135
	v_lshl_add_u64 v[70:71], v[148:149], 0, s[54:55]
	v_lshl_add_u64 v[70:71], v[70:71], 2, v[82:83]
	global_store_dwordx4 v[70:71], v[64:67], off offset:576
.LBB0_437:
	s_or_b64 exec, exec, s[62:63]
	v_or_b32_e32 v70, 0x90, v148
	s_and_saveexec_b64 s[8:9], s[60:61]
	s_cbranch_execz .LBB0_439
	v_add_u32_e32 v71, s54, v70
	v_ashrrev_i32_e32 v71, 7, v71
	v_add_u32_e32 v72, s96, v71
	s_and_b64 s[60:61], s[52:53], exec
	v_ashrrev_i32_e32 v73, 31, v72
	s_cselect_b32 s61, s76, s74
	s_cselect_b32 s60, s75, s73
	v_lshlrev_b64 v[72:73], 20, v[72:73]
	v_lshl_add_u64 v[72:73], s[60:61], 0, v[72:73]
	v_and_b32_e32 v71, 0x7c, v70
	v_lshl_add_u64 v[72:73], v[72:73], 0, v[134:135]
	v_lshlrev_b32_e32 v134, 1, v71
	v_lshl_add_u64 v[72:73], v[72:73], 0, v[134:135]
	v_lshl_add_u64 v[196:197], v[194:195], 0, v[188:189]
	global_store_dwordx4 v[196:197], v[182:185], off

.LBB0_448:
	v_mov_b64_e32 v[72:73], s[20:21]
	s_waitcnt vmcnt(0)
	v_pk_mul_f32 v[62:63], v[62:63], v[66:67] op_sel_hi:[1,0]
	v_pk_mul_f32 v[60:61], v[60:61], v[66:67] op_sel_hi:[1,0]
	v_mad_i64_i32 v[72:73], s[60:61], v64, s90, v[72:73]
	v_lshlrev_b32_e32 v134, 1, v148
	v_cmp_ne_u64_e64 s[8:9], 0, v[68:69]
	v_cvt_pk_bf16_f32 v70, v60, v61
	v_cvt_pk_bf16_f32 v71, v62, v63
	v_lshl_add_u64 v[72:73], v[72:73], 0, v[134:135]
	v_mov_b32_e32 v182, v70
	v_mov_b32_e32 v183, v71
	s_and_saveexec_b64 s[60:61], s[8:9]
	s_cbranch_execz .LBB0_450
	v_add_u32_e32 v74, s54, v148
	v_ashrrev_i32_e32 v75, 31, v74
	v_lshl_add_u64 v[74:75], v[74:75], 2, v[68:69]
	global_store_dwordx4 v[74:75], v[60:63], off
.LBB0_450:
	s_or_b64 exec, exec, s[60:61]
	v_lshlrev_b32_e32 v67, 7, v64
	v_cmp_gt_i32_e32 vcc, s72, v64
	v_and_b32_e32 v67, 0x7e780, v67
	s_and_b64 s[60:61], s[56:57], vcc
	v_lshlrev_b32_e32 v134, 1, v67
	s_and_saveexec_b64 s[62:63], s[60:61]
	s_cbranch_execz .LBB0_452
	s_add_i32 s10, s54, s45
	s_and_b64 vcc, s[52:53], exec
	s_cselect_b32 s11, s76, s74
	s_cselect_b32 s33, s75, s73
	s_ashr_i32 s10, s10, 7
	s_add_i32 vcc_lo, s10, s95
	s_ashr_i32 vcc_hi, vcc_lo, 31
	s_lshl_b64 vcc, vcc, 20
	s_add_u32 vcc_lo, s33, vcc_lo
	s_addc_u32 vcc_hi, s11, vcc_hi
	v_lshl_add_u64 v[74:75], vcc, 0, v[134:135]
	v_lshlrev_b32_e32 v76, 1, v136
	v_mov_b32_e32 v77, v135
	v_lshl_add_u64 v[74:75], v[74:75], 0, v[76:77]
	v_mov_b32_e32 v194, v74
	v_mov_b32_e32 v195, v75

.LBB0_454:
	s_or_b64 exec, exec, s[62:63]
	v_mov_b32_e32 v67, v66
	v_mov_b32_e32 v60, v66
	v_mov_b32_e32 v61, v66
	v_pk_mul_f32 v[58:59], v[58:59], v[60:61]
	v_pk_mul_f32 v[56:57], v[56:57], v[66:67]
	v_cvt_pk_bf16_f32 v61, v58, v59
	v_cvt_pk_bf16_f32 v60, v56, v57
	v_mov_b32_e32 v184, v60
	v_mov_b32_e32 v185, v61
	s_nop 1
	v_permlane16_swap_b32_e32 v182, v184
	v_permlane16_swap_b32_e32 v183, v185
	s_mov_b64 exec, s[98:99]
	v_lshl_add_u64 v[186:187], v[72:73], 0, v[188:189]
	global_store_dwordx4 v[186:187], v[182:185], off
	s_mov_b64 exec, -1
	s_and_saveexec_b64 s[62:63], s[8:9]
	s_cbranch_execz .LBB0_456
	s_ashr_i32 s55, s54, 31
	v_mov_b32_e32 v149, v135
	v_lshl_add_u64 v[62:63], v[148:149], 0, s[54:55]
	v_lshl_add_u64 v[62:63], v[62:63], 2, v[68:69]
	global_store_dwordx4 v[62:63], v[56:59], off offset:64
.LBB0_456:
	s_or_b64 exec, exec, s[62:63]
	v_or_b32_e32 v62, 16, v148
	s_and_saveexec_b64 s[62:63], s[60:61]
	s_cbranch_execz .LBB0_458
	s_add_i32 s10, s54, s45
	s_and_b64 vcc, s[52:53], exec
	s_cselect_b32 s11, s76, s74
	s_cselect_b32 s33, s75, s73
	s_ashr_i32 s10, s10, 7
	s_add_i32 vcc_lo, s10, s95
	s_ashr_i32 vcc_hi, vcc_lo, 31
	s_lshl_b64 vcc, vcc, 20
	s_add_u32 vcc_lo, s33, vcc_lo
	s_addc_u32 vcc_hi, s11, vcc_hi
	v_and_b32_e32 v63, 0x7c, v62
	v_lshl_add_u64 v[74:75], vcc, 0, v[134:135]
	v_lshlrev_b32_e32 v76, 1, v63
	v_mov_b32_e32 v77, v135
	v_lshl_add_u64 v[74:75], v[74:75], 0, v[76:77]
	v_lshl_add_u64 v[196:197], v[194:195], 0, v[188:189]
	global_store_dwordx4 v[196:197], v[182:185], off

.LBB0_460:
	s_or_b64 exec, exec, s[62:63]
	s_nop 0
	v_mov_b32_e32 v56, v66
	v_mov_b32_e32 v57, v66
	v_pk_mul_f32 v[54:55], v[54:55], v[56:57]
	v_pk_mul_f32 v[52:53], v[52:53], v[66:67]
	v_cvt_pk_bf16_f32 v57, v54, v55
	v_cvt_pk_bf16_f32 v56, v52, v53
	v_mov_b32_e32 v182, v56
	v_mov_b32_e32 v183, v57
	s_and_saveexec_b64 s[62:63], s[8:9]
	s_cbranch_execz .LBB0_462
	s_ashr_i32 s55, s54, 31
	v_mov_b32_e32 v149, v135
	v_lshl_add_u64 v[58:59], v[148:149], 0, s[54:55]
	v_lshl_add_u64 v[58:59], v[58:59], 2, v[68:69]
	global_store_dwordx4 v[58:59], v[52:55], off offset:512
.LBB0_462:
	s_or_b64 exec, exec, s[62:63]
	v_or_b32_e32 v58, 0x80, v148
	s_and_saveexec_b64 s[62:63], s[60:61]
	s_cbranch_execz .LBB0_464
	v_add_u32_e32 v59, s54, v58
	v_ashrrev_i32_e32 v59, 7, v59
	v_add_u32_e32 v60, s95, v59
	s_and_b64 vcc, s[52:53], exec
	v_ashrrev_i32_e32 v61, 31, v60
	s_cselect_b32 vcc_hi, s76, s74
	s_cselect_b32 vcc_lo, s75, s73
	v_lshlrev_b64 v[60:61], 20, v[60:61]
	v_lshl_add_u64 v[60:61], vcc, 0, v[60:61]
	v_lshl_add_u64 v[60:61], v[60:61], 0, v[134:135]
	v_lshlrev_b32_e32 v62, 1, v136
	v_mov_b32_e32 v63, v135
	v_lshl_add_u64 v[60:61], v[60:61], 0, v[62:63]
	v_mov_b32_e32 v194, v60
	v_mov_b32_e32 v195, v61

.LBB0_466:
	s_or_b64 exec, exec, s[62:63]
	s_nop 0
	v_mov_b32_e32 v52, v66
	v_mov_b32_e32 v53, v66
	v_pk_mul_f32 v[50:51], v[50:51], v[52:53]
	v_pk_mul_f32 v[48:49], v[48:49], v[66:67]
	v_cvt_pk_bf16_f32 v53, v50, v51
	v_cvt_pk_bf16_f32 v52, v48, v49
	v_mov_b32_e32 v184, v52
	v_mov_b32_e32 v185, v53
	s_nop 1
	v_permlane16_swap_b32_e32 v182, v184
	v_permlane16_swap_b32_e32 v183, v185
	s_mov_b64 exec, s[98:99]
	v_lshl_add_u64 v[186:187], v[72:73], 0, v[188:189]
	global_store_dwordx4 v[186:187], v[182:185], off offset:256
	s_mov_b64 exec, -1
	s_and_saveexec_b64 s[62:63], s[8:9]
	s_cbranch_execz .LBB0_468
	s_ashr_i32 s55, s54, 31
	v_mov_b32_e32 v149, v135
	v_lshl_add_u64 v[54:55], v[148:149], 0, s[54:55]
	v_lshl_add_u64 v[54:55], v[54:55], 2, v[68:69]
	global_store_dwordx4 v[54:55], v[48:51], off offset:576
.LBB0_468:
	s_or_b64 exec, exec, s[62:63]
	v_or_b32_e32 v54, 0x90, v148
	s_and_saveexec_b64 s[8:9], s[60:61]
	s_cbranch_execz .LBB0_470
	v_add_u32_e32 v55, s54, v54
	v_ashrrev_i32_e32 v55, 7, v55
	v_add_u32_e32 v56, s95, v55
	s_and_b64 s[60:61], s[52:53], exec
	v_ashrrev_i32_e32 v57, 31, v56
	s_cselect_b32 s61, s76, s74
	s_cselect_b32 s60, s75, s73
	v_lshlrev_b64 v[56:57], 20, v[56:57]
	v_lshl_add_u64 v[56:57], s[60:61], 0, v[56:57]
	v_and_b32_e32 v55, 0x7c, v54
	v_lshl_add_u64 v[56:57], v[56:57], 0, v[134:135]
	v_lshlrev_b32_e32 v134, 1, v55
	v_lshl_add_u64 v[56:57], v[56:57], 0, v[134:135]
	v_lshl_add_u64 v[196:197], v[194:195], 0, v[188:189]
	global_store_dwordx4 v[196:197], v[182:185], off

.LBB0_479:
	v_mov_b64_e32 v[54:55], s[20:21]
	s_waitcnt vmcnt(0)
	v_pk_mul_f32 v[46:47], v[46:47], v[48:49] op_sel_hi:[1,0]
	v_pk_mul_f32 v[44:45], v[44:45], v[48:49] op_sel_hi:[1,0]
	v_mad_i64_i32 v[54:55], s[60:61], v52, s90, v[54:55]
	v_lshlrev_b32_e32 v134, 1, v148
	v_cmp_ne_u64_e64 s[8:9], 0, v[50:51]
	v_cvt_pk_bf16_f32 v56, v44, v45
	v_cvt_pk_bf16_f32 v57, v46, v47
	v_lshl_add_u64 v[54:55], v[54:55], 0, v[134:135]
	v_mov_b32_e32 v182, v56
	v_mov_b32_e32 v183, v57
	s_and_saveexec_b64 s[60:61], s[8:9]
	s_cbranch_execz .LBB0_481
	v_add_u32_e32 v58, s54, v148
	v_ashrrev_i32_e32 v59, 31, v58
	v_lshl_add_u64 v[58:59], v[58:59], 2, v[50:51]
	global_store_dwordx4 v[58:59], v[44:47], off
.LBB0_481:
	s_or_b64 exec, exec, s[60:61]
	v_lshlrev_b32_e32 v49, 7, v52
	v_cmp_gt_i32_e32 vcc, s72, v52
	v_and_b32_e32 v49, 0x7ff80, v49
	s_and_b64 s[60:61], s[56:57], vcc
	v_lshlrev_b32_e32 v134, 1, v49
	s_and_saveexec_b64 s[62:63], s[60:61]
	s_cbranch_execz .LBB0_483
	s_add_i32 s10, s54, s45
	s_and_b64 vcc, s[52:53], exec
	s_cselect_b32 s11, s76, s74
	s_cselect_b32 s33, s75, s73
	s_ashr_i32 s10, s10, 7
	s_add_i32 vcc_lo, s10, s95
	s_ashr_i32 vcc_hi, vcc_lo, 31
	s_lshl_b64 vcc, vcc, 20
	s_add_u32 vcc_lo, s33, vcc_lo
	s_addc_u32 vcc_hi, s11, vcc_hi
	v_lshl_add_u64 v[58:59], vcc, 0, v[134:135]
	v_lshlrev_b32_e32 v60, 1, v136
	v_mov_b32_e32 v61, v135
	v_lshl_add_u64 v[58:59], v[58:59], 0, v[60:61]
	v_mov_b32_e32 v194, v58
	v_mov_b32_e32 v195, v59

.LBB0_485:
	s_or_b64 exec, exec, s[62:63]
	v_mov_b32_e32 v49, v48
	v_mov_b32_e32 v44, v48
	v_mov_b32_e32 v45, v48
	v_pk_mul_f32 v[42:43], v[42:43], v[44:45]
	v_pk_mul_f32 v[40:41], v[40:41], v[48:49]
	v_cvt_pk_bf16_f32 v45, v42, v43
	v_cvt_pk_bf16_f32 v44, v40, v41
	v_mov_b32_e32 v184, v44
	v_mov_b32_e32 v185, v45
	s_nop 1
	v_permlane16_swap_b32_e32 v182, v184
	v_permlane16_swap_b32_e32 v183, v185
	s_mov_b64 exec, s[98:99]
	v_lshl_add_u64 v[186:187], v[54:55], 0, v[188:189]
	global_store_dwordx4 v[186:187], v[182:185], off
	s_mov_b64 exec, -1
	s_and_saveexec_b64 s[62:63], s[8:9]
	s_cbranch_execz .LBB0_487
	s_ashr_i32 s55, s54, 31
	v_mov_b32_e32 v149, v135
	v_lshl_add_u64 v[46:47], v[148:149], 0, s[54:55]
	v_lshl_add_u64 v[46:47], v[46:47], 2, v[50:51]
	global_store_dwordx4 v[46:47], v[40:43], off offset:64
.LBB0_487:
	s_or_b64 exec, exec, s[62:63]
	v_or_b32_e32 v46, 16, v148
	s_and_saveexec_b64 s[62:63], s[60:61]
	s_cbranch_execz .LBB0_489
	s_add_i32 s10, s54, s45
	s_and_b64 vcc, s[52:53], exec
	s_cselect_b32 s11, s76, s74
	s_cselect_b32 s33, s75, s73
	s_ashr_i32 s10, s10, 7
	s_add_i32 vcc_lo, s10, s95
	s_ashr_i32 vcc_hi, vcc_lo, 31
	s_lshl_b64 vcc, vcc, 20
	s_add_u32 vcc_lo, s33, vcc_lo
	s_addc_u32 vcc_hi, s11, vcc_hi
	v_and_b32_e32 v47, 0x7c, v46
	v_lshl_add_u64 v[56:57], vcc, 0, v[134:135]
	v_lshlrev_b32_e32 v58, 1, v47
	v_mov_b32_e32 v59, v135
	v_lshl_add_u64 v[56:57], v[56:57], 0, v[58:59]
	v_lshl_add_u64 v[196:197], v[194:195], 0, v[188:189]
	global_store_dwordx4 v[196:197], v[182:185], off

.LBB0_491:
	s_or_b64 exec, exec, s[62:63]
	s_nop 0
	v_mov_b32_e32 v40, v48
	v_mov_b32_e32 v41, v48
	v_pk_mul_f32 v[38:39], v[38:39], v[40:41]
	v_pk_mul_f32 v[36:37], v[36:37], v[48:49]
	v_cvt_pk_bf16_f32 v41, v38, v39
	v_cvt_pk_bf16_f32 v40, v36, v37
	v_mov_b32_e32 v182, v40
	v_mov_b32_e32 v183, v41
	s_and_saveexec_b64 s[62:63], s[8:9]
	s_cbranch_execz .LBB0_493
	s_ashr_i32 s55, s54, 31
	v_mov_b32_e32 v149, v135
	v_lshl_add_u64 v[42:43], v[148:149], 0, s[54:55]
	v_lshl_add_u64 v[42:43], v[42:43], 2, v[50:51]
	global_store_dwordx4 v[42:43], v[36:39], off offset:512
.LBB0_493:
	s_or_b64 exec, exec, s[62:63]
	v_or_b32_e32 v42, 0x80, v148
	s_and_saveexec_b64 s[62:63], s[60:61]
	s_cbranch_execz .LBB0_495
	v_add_u32_e32 v43, s54, v42
	v_ashrrev_i32_e32 v43, 7, v43
	v_add_u32_e32 v44, s95, v43
	s_and_b64 vcc, s[52:53], exec
	v_ashrrev_i32_e32 v45, 31, v44
	s_cselect_b32 vcc_hi, s76, s74
	s_cselect_b32 vcc_lo, s75, s73
	v_lshlrev_b64 v[44:45], 20, v[44:45]
	v_lshl_add_u64 v[44:45], vcc, 0, v[44:45]
	v_lshl_add_u64 v[44:45], v[44:45], 0, v[134:135]
	v_lshlrev_b32_e32 v46, 1, v136
	v_mov_b32_e32 v47, v135
	v_lshl_add_u64 v[44:45], v[44:45], 0, v[46:47]
	v_mov_b32_e32 v194, v44
	v_mov_b32_e32 v195, v45

.LBB0_497:
	s_or_b64 exec, exec, s[62:63]
	s_nop 0
	v_mov_b32_e32 v36, v48
	v_mov_b32_e32 v37, v48
	v_pk_mul_f32 v[34:35], v[34:35], v[36:37]
	v_pk_mul_f32 v[32:33], v[32:33], v[48:49]
	v_cvt_pk_bf16_f32 v37, v34, v35
	v_cvt_pk_bf16_f32 v36, v32, v33
	v_mov_b32_e32 v184, v36
	v_mov_b32_e32 v185, v37
	s_nop 1
	v_permlane16_swap_b32_e32 v182, v184
	v_permlane16_swap_b32_e32 v183, v185
	s_mov_b64 exec, s[98:99]
	v_lshl_add_u64 v[186:187], v[54:55], 0, v[188:189]
	global_store_dwordx4 v[186:187], v[182:185], off offset:256
	s_mov_b64 exec, -1
	s_and_saveexec_b64 s[62:63], s[8:9]
	s_cbranch_execz .LBB0_499
	s_ashr_i32 s55, s54, 31
	v_mov_b32_e32 v149, v135
	v_lshl_add_u64 v[38:39], v[148:149], 0, s[54:55]
	v_lshl_add_u64 v[38:39], v[38:39], 2, v[50:51]
	global_store_dwordx4 v[38:39], v[32:35], off offset:576
.LBB0_499:
	s_or_b64 exec, exec, s[62:63]
	v_or_b32_e32 v38, 0x90, v148
	s_and_saveexec_b64 s[8:9], s[60:61]
	s_cbranch_execz .LBB0_501
	v_add_u32_e32 v39, s54, v38
	v_ashrrev_i32_e32 v39, 7, v39
	v_add_u32_e32 v40, s95, v39
	s_and_b64 s[60:61], s[52:53], exec
	v_ashrrev_i32_e32 v41, 31, v40
	s_cselect_b32 s61, s76, s74
	s_cselect_b32 s60, s75, s73
	v_lshlrev_b64 v[40:41], 20, v[40:41]
	v_lshl_add_u64 v[40:41], s[60:61], 0, v[40:41]
	v_and_b32_e32 v39, 0x7c, v38
	v_lshl_add_u64 v[40:41], v[40:41], 0, v[134:135]
	v_lshlrev_b32_e32 v134, 1, v39
	v_lshl_add_u64 v[40:41], v[40:41], 0, v[134:135]
	v_lshl_add_u64 v[196:197], v[194:195], 0, v[188:189]
	global_store_dwordx4 v[196:197], v[182:185], off

.LBB0_510:
	v_mov_b64_e32 v[38:39], s[20:21]
	s_waitcnt vmcnt(0)
	v_pk_mul_f32 v[30:31], v[30:31], v[32:33] op_sel_hi:[1,0]
	v_pk_mul_f32 v[28:29], v[28:29], v[32:33] op_sel_hi:[1,0]
	v_mad_i64_i32 v[38:39], s[60:61], v36, s90, v[38:39]
	v_lshlrev_b32_e32 v134, 1, v148
	v_cmp_ne_u64_e64 s[8:9], 0, v[34:35]
	v_cvt_pk_bf16_f32 v40, v28, v29
	v_cvt_pk_bf16_f32 v41, v30, v31
	v_lshl_add_u64 v[38:39], v[38:39], 0, v[134:135]
	v_mov_b32_e32 v182, v40
	v_mov_b32_e32 v183, v41
	s_and_saveexec_b64 s[60:61], s[8:9]
	s_cbranch_execz .LBB0_512
	v_add_u32_e32 v42, s54, v148
	v_ashrrev_i32_e32 v43, 31, v42
	v_lshl_add_u64 v[42:43], v[42:43], 2, v[34:35]
	global_store_dwordx4 v[42:43], v[28:31], off
.LBB0_512:
	s_or_b64 exec, exec, s[60:61]
	v_lshlrev_b32_e32 v33, 7, v36
	v_cmp_gt_i32_e32 vcc, s72, v36
	v_and_b32_e32 v33, 0x7ff80, v33
	s_and_b64 s[60:61], s[56:57], vcc
	v_lshlrev_b32_e32 v134, 1, v33
	s_and_saveexec_b64 s[62:63], s[60:61]
	s_cbranch_execz .LBB0_514
	s_add_i32 s10, s54, s45
	s_and_b64 vcc, s[52:53], exec
	s_cselect_b32 s11, s76, s74
	s_cselect_b32 s33, s75, s73
	s_ashr_i32 s10, s10, 7
	s_add_i32 vcc_lo, s10, s95
	s_ashr_i32 vcc_hi, vcc_lo, 31
	s_lshl_b64 vcc, vcc, 20
	s_add_u32 vcc_lo, s33, vcc_lo
	s_addc_u32 vcc_hi, s11, vcc_hi
	v_lshl_add_u64 v[42:43], vcc, 0, v[134:135]
	v_lshlrev_b32_e32 v44, 1, v136
	v_mov_b32_e32 v45, v135
	v_lshl_add_u64 v[42:43], v[42:43], 0, v[44:45]
	v_mov_b32_e32 v194, v42
	v_mov_b32_e32 v195, v43

.LBB0_516:
	s_or_b64 exec, exec, s[62:63]
	v_mov_b32_e32 v33, v32
	v_mov_b32_e32 v28, v32
	v_mov_b32_e32 v29, v32
	v_pk_mul_f32 v[26:27], v[26:27], v[28:29]
	v_pk_mul_f32 v[24:25], v[24:25], v[32:33]
	v_cvt_pk_bf16_f32 v29, v26, v27
	v_cvt_pk_bf16_f32 v28, v24, v25
	v_mov_b32_e32 v184, v28
	v_mov_b32_e32 v185, v29
	s_nop 1
	v_permlane16_swap_b32_e32 v182, v184
	v_permlane16_swap_b32_e32 v183, v185
	s_mov_b64 exec, s[98:99]
	v_lshl_add_u64 v[186:187], v[38:39], 0, v[188:189]
	global_store_dwordx4 v[186:187], v[182:185], off
	s_mov_b64 exec, -1
	s_and_saveexec_b64 s[62:63], s[8:9]
	s_cbranch_execz .LBB0_518
	s_ashr_i32 s55, s54, 31
	v_mov_b32_e32 v149, v135
	v_lshl_add_u64 v[30:31], v[148:149], 0, s[54:55]
	v_lshl_add_u64 v[30:31], v[30:31], 2, v[34:35]
	global_store_dwordx4 v[30:31], v[24:27], off offset:64
.LBB0_518:
	s_or_b64 exec, exec, s[62:63]
	v_or_b32_e32 v30, 16, v148
	s_and_saveexec_b64 s[62:63], s[60:61]
	s_cbranch_execz .LBB0_520
	s_add_i32 s10, s54, s45
	s_and_b64 vcc, s[52:53], exec
	s_cselect_b32 s11, s76, s74
	s_cselect_b32 s33, s75, s73
	s_ashr_i32 s10, s10, 7
	s_add_i32 vcc_lo, s10, s95
	s_ashr_i32 vcc_hi, vcc_lo, 31
	s_lshl_b64 vcc, vcc, 20
	s_add_u32 vcc_lo, s33, vcc_lo
	s_addc_u32 vcc_hi, s11, vcc_hi
	v_and_b32_e32 v31, 0x7c, v30
	v_lshl_add_u64 v[40:41], vcc, 0, v[134:135]
	v_lshlrev_b32_e32 v42, 1, v31
	v_mov_b32_e32 v43, v135
	v_lshl_add_u64 v[40:41], v[40:41], 0, v[42:43]
	v_lshl_add_u64 v[196:197], v[194:195], 0, v[188:189]
	global_store_dwordx4 v[196:197], v[182:185], off

.LBB0_522:
	s_or_b64 exec, exec, s[62:63]
	s_nop 0
	v_mov_b32_e32 v24, v32
	v_mov_b32_e32 v25, v32
	v_pk_mul_f32 v[22:23], v[22:23], v[24:25]
	v_pk_mul_f32 v[20:21], v[20:21], v[32:33]
	v_cvt_pk_bf16_f32 v25, v22, v23
	v_cvt_pk_bf16_f32 v24, v20, v21
	v_mov_b32_e32 v182, v24
	v_mov_b32_e32 v183, v25
	s_and_saveexec_b64 s[62:63], s[8:9]
	s_cbranch_execz .LBB0_524
	s_ashr_i32 s55, s54, 31
	v_mov_b32_e32 v149, v135
	v_lshl_add_u64 v[26:27], v[148:149], 0, s[54:55]
	v_lshl_add_u64 v[26:27], v[26:27], 2, v[34:35]
	global_store_dwordx4 v[26:27], v[20:23], off offset:512
.LBB0_524:
	s_or_b64 exec, exec, s[62:63]
	v_or_b32_e32 v26, 0x80, v148
	s_and_saveexec_b64 s[62:63], s[60:61]
	s_cbranch_execz .LBB0_526
	v_add_u32_e32 v27, s54, v26
	v_ashrrev_i32_e32 v27, 7, v27
	v_add_u32_e32 v28, s95, v27
	s_and_b64 vcc, s[52:53], exec
	v_ashrrev_i32_e32 v29, 31, v28
	s_cselect_b32 vcc_hi, s76, s74
	s_cselect_b32 vcc_lo, s75, s73
	v_lshlrev_b64 v[28:29], 20, v[28:29]
	v_lshl_add_u64 v[28:29], vcc, 0, v[28:29]
	v_lshl_add_u64 v[28:29], v[28:29], 0, v[134:135]
	v_lshlrev_b32_e32 v30, 1, v136
	v_mov_b32_e32 v31, v135
	v_lshl_add_u64 v[28:29], v[28:29], 0, v[30:31]
	v_mov_b32_e32 v194, v28
	v_mov_b32_e32 v195, v29

.LBB0_528:
	s_or_b64 exec, exec, s[62:63]
	s_nop 0
	v_mov_b32_e32 v20, v32
	v_mov_b32_e32 v21, v32
	v_pk_mul_f32 v[18:19], v[18:19], v[20:21]
	v_pk_mul_f32 v[16:17], v[16:17], v[32:33]
	v_cvt_pk_bf16_f32 v21, v18, v19
	v_cvt_pk_bf16_f32 v20, v16, v17
	v_mov_b32_e32 v184, v20
	v_mov_b32_e32 v185, v21
	s_nop 1
	v_permlane16_swap_b32_e32 v182, v184
	v_permlane16_swap_b32_e32 v183, v185
	s_mov_b64 exec, s[98:99]
	v_lshl_add_u64 v[186:187], v[38:39], 0, v[188:189]
	global_store_dwordx4 v[186:187], v[182:185], off offset:256
	s_mov_b64 exec, -1
	s_and_saveexec_b64 s[62:63], s[8:9]
	s_cbranch_execz .LBB0_530
	s_ashr_i32 s55, s54, 31
	v_mov_b32_e32 v149, v135
	v_lshl_add_u64 v[22:23], v[148:149], 0, s[54:55]
	v_lshl_add_u64 v[22:23], v[22:23], 2, v[34:35]
	global_store_dwordx4 v[22:23], v[16:19], off offset:576
.LBB0_530:
	s_or_b64 exec, exec, s[62:63]
	v_or_b32_e32 v22, 0x90, v148
	s_and_saveexec_b64 s[8:9], s[60:61]
	s_cbranch_execz .LBB0_532
	v_add_u32_e32 v23, s54, v22
	v_ashrrev_i32_e32 v23, 7, v23
	v_add_u32_e32 v24, s95, v23
	s_and_b64 s[60:61], s[52:53], exec
	v_ashrrev_i32_e32 v25, 31, v24
	s_cselect_b32 s61, s76, s74
	s_cselect_b32 s60, s75, s73
	v_lshlrev_b64 v[24:25], 20, v[24:25]
	v_lshl_add_u64 v[24:25], s[60:61], 0, v[24:25]
	v_and_b32_e32 v23, 0x7c, v22
	v_lshl_add_u64 v[24:25], v[24:25], 0, v[134:135]
	v_lshlrev_b32_e32 v134, 1, v23
	v_lshl_add_u64 v[24:25], v[24:25], 0, v[134:135]
	v_lshl_add_u64 v[196:197], v[194:195], 0, v[188:189]
	global_store_dwordx4 v[196:197], v[182:185], off

.LBB0_541:
	v_mov_b64_e32 v[24:25], s[20:21]
	s_waitcnt vmcnt(0)
	v_pk_mul_f32 v[14:15], v[14:15], v[16:17] op_sel_hi:[1,0]
	v_pk_mul_f32 v[12:13], v[12:13], v[16:17] op_sel_hi:[1,0]
	v_mad_i64_i32 v[24:25], s[58:59], v20, s90, v[24:25]
	v_lshlrev_b32_e32 v134, 1, v148
	v_cmp_ne_u64_e64 s[6:7], 0, v[18:19]
	v_cvt_pk_bf16_f32 v22, v12, v13
	v_cvt_pk_bf16_f32 v23, v14, v15
	v_lshl_add_u64 v[24:25], v[24:25], 0, v[134:135]
	v_mov_b32_e32 v182, v22
	v_mov_b32_e32 v183, v23
	s_and_saveexec_b64 s[58:59], s[6:7]
	s_cbranch_execz .LBB0_543
	v_add_u32_e32 v26, s54, v148
	v_ashrrev_i32_e32 v27, 31, v26
	v_lshl_add_u64 v[26:27], v[26:27], 2, v[18:19]
	global_store_dwordx4 v[26:27], v[12:15], off
.LBB0_543:
	s_or_b64 exec, exec, s[58:59]
	v_lshlrev_b32_e32 v17, 7, v20
	v_cmp_gt_i32_e32 vcc, s72, v20
	v_and_b32_e32 v17, 0x7ff80, v17
	s_and_b64 s[56:57], s[56:57], vcc
	v_lshlrev_b32_e32 v134, 1, v17
	v_lshlrev_b32_e32 v26, 1, v136
	s_and_saveexec_b64 s[58:59], s[56:57]
	s_cbranch_execz .LBB0_545
	s_add_i32 s10, s54, s45
	s_and_b64 s[60:61], s[52:53], exec
	s_cselect_b32 s11, s76, s74
	s_cselect_b32 s33, s75, s73
	s_ashr_i32 s10, s10, 7
	s_add_i32 s60, s10, s95
	s_ashr_i32 s61, s60, 31
	s_lshl_b64 s[60:61], s[60:61], 20
	s_add_u32 s60, s33, s60
	s_addc_u32 s61, s11, s61
	v_lshl_add_u64 v[28:29], s[60:61], 0, v[134:135]
	v_mov_b32_e32 v27, v135
	v_lshl_add_u64 v[28:29], v[28:29], 0, v[26:27]
	v_mov_b32_e32 v194, v28
	v_mov_b32_e32 v195, v29

.LBB0_547:
	s_or_b64 exec, exec, s[58:59]
	v_mov_b32_e32 v17, v16
	v_mov_b32_e32 v12, v16
	v_mov_b32_e32 v13, v16
	v_pk_mul_f32 v[10:11], v[10:11], v[12:13]
	v_pk_mul_f32 v[8:9], v[8:9], v[16:17]
	v_cvt_pk_bf16_f32 v13, v10, v11
	v_cvt_pk_bf16_f32 v12, v8, v9
	v_mov_b32_e32 v184, v12
	v_mov_b32_e32 v185, v13
	s_nop 1
	v_permlane16_swap_b32_e32 v182, v184
	v_permlane16_swap_b32_e32 v183, v185
	s_mov_b64 exec, s[98:99]
	v_lshl_add_u64 v[186:187], v[24:25], 0, v[188:189]
	global_store_dwordx4 v[186:187], v[182:185], off
	s_mov_b64 exec, -1
	s_and_saveexec_b64 s[58:59], s[6:7]
	s_cbranch_execz .LBB0_549
	s_ashr_i32 s55, s54, 31
	v_mov_b32_e32 v149, v135
	v_lshl_add_u64 v[14:15], v[148:149], 0, s[54:55]
	v_lshl_add_u64 v[14:15], v[14:15], 2, v[18:19]
	global_store_dwordx4 v[14:15], v[8:11], off offset:64
.LBB0_549:
	s_or_b64 exec, exec, s[58:59]
	v_or_b32_e32 v14, 16, v148
	s_and_saveexec_b64 s[58:59], s[56:57]
	s_cbranch_execz .LBB0_551
	s_add_i32 s10, s54, s45
	s_and_b64 s[60:61], s[52:53], exec
	s_cselect_b32 s11, s76, s74
	s_cselect_b32 s33, s75, s73
	s_ashr_i32 s10, s10, 7
	s_add_i32 s60, s10, s95
	s_ashr_i32 s61, s60, 31
	s_lshl_b64 s[60:61], s[60:61], 20
	s_add_u32 s60, s33, s60
	s_addc_u32 s61, s11, s61
	v_and_b32_e32 v15, 0x7c, v14
	v_lshl_add_u64 v[28:29], s[60:61], 0, v[134:135]
	v_lshlrev_b32_e32 v30, 1, v15
	v_mov_b32_e32 v31, v135
	v_lshl_add_u64 v[28:29], v[28:29], 0, v[30:31]
	v_lshl_add_u64 v[196:197], v[194:195], 0, v[188:189]
	global_store_dwordx4 v[196:197], v[182:185], off

.LBB0_553:
	s_or_b64 exec, exec, s[58:59]
	s_nop 0
	v_mov_b32_e32 v8, v16
	v_mov_b32_e32 v9, v16
	v_pk_mul_f32 v[6:7], v[6:7], v[8:9]
	v_pk_mul_f32 v[4:5], v[4:5], v[16:17]
	v_cvt_pk_bf16_f32 v9, v6, v7
	v_cvt_pk_bf16_f32 v8, v4, v5
	v_mov_b32_e32 v182, v8
	v_mov_b32_e32 v183, v9
	s_and_saveexec_b64 s[58:59], s[6:7]
	s_cbranch_execz .LBB0_555
	s_ashr_i32 s55, s54, 31
	v_mov_b32_e32 v149, v135
	v_lshl_add_u64 v[10:11], v[148:149], 0, s[54:55]
	v_lshl_add_u64 v[10:11], v[10:11], 2, v[18:19]
	global_store_dwordx4 v[10:11], v[4:7], off offset:512
.LBB0_555:
	s_or_b64 exec, exec, s[58:59]
	v_or_b32_e32 v10, 0x80, v148
	s_and_saveexec_b64 s[58:59], s[56:57]
	s_cbranch_execz .LBB0_557
	v_add_u32_e32 v11, s54, v10
	v_ashrrev_i32_e32 v11, 7, v11
	v_add_u32_e32 v12, s95, v11
	s_and_b64 s[60:61], s[52:53], exec
	v_ashrrev_i32_e32 v13, 31, v12
	s_cselect_b32 s61, s76, s74
	s_cselect_b32 s60, s75, s73
	v_lshlrev_b64 v[12:13], 20, v[12:13]
	v_lshl_add_u64 v[12:13], s[60:61], 0, v[12:13]
	v_lshl_add_u64 v[12:13], v[12:13], 0, v[134:135]
	v_mov_b32_e32 v27, v135
	v_lshl_add_u64 v[12:13], v[12:13], 0, v[26:27]
	v_mov_b32_e32 v194, v12
	v_mov_b32_e32 v195, v13

.LBB0_559:
	s_or_b64 exec, exec, s[58:59]
	s_nop 0
	v_mov_b32_e32 v4, v16
	v_mov_b32_e32 v5, v16
	v_pk_mul_f32 v[2:3], v[2:3], v[4:5]
	v_pk_mul_f32 v[0:1], v[0:1], v[16:17]
	v_cvt_pk_bf16_f32 v5, v2, v3
	v_cvt_pk_bf16_f32 v4, v0, v1
	v_mov_b32_e32 v184, v4
	v_mov_b32_e32 v185, v5
	s_nop 1
	v_permlane16_swap_b32_e32 v182, v184
	v_permlane16_swap_b32_e32 v183, v185
	s_mov_b64 exec, s[98:99]
	v_lshl_add_u64 v[186:187], v[24:25], 0, v[188:189]
	global_store_dwordx4 v[186:187], v[182:185], off offset:256
	s_mov_b64 exec, -1
	s_and_saveexec_b64 s[58:59], s[6:7]
	s_cbranch_execz .LBB0_561
	s_ashr_i32 s55, s54, 31
	v_mov_b32_e32 v149, v135
	v_lshl_add_u64 v[6:7], v[148:149], 0, s[54:55]
	v_lshl_add_u64 v[6:7], v[6:7], 2, v[18:19]
	global_store_dwordx4 v[6:7], v[0:3], off offset:576
.LBB0_561:
	s_or_b64 exec, exec, s[58:59]
	v_or_b32_e32 v6, 0x90, v148
	s_and_saveexec_b64 s[6:7], s[56:57]
	s_cbranch_execz .LBB0_563
	v_add_u32_e32 v7, s54, v6
	v_ashrrev_i32_e32 v7, 7, v7
	v_add_u32_e32 v8, s95, v7
	s_and_b64 s[52:53], s[52:53], exec
	v_ashrrev_i32_e32 v9, 31, v8
	s_cselect_b32 s53, s76, s74
	s_cselect_b32 s52, s75, s73
	v_lshlrev_b64 v[8:9], 20, v[8:9]
	v_lshl_add_u64 v[8:9], s[52:53], 0, v[8:9]
	v_and_b32_e32 v7, 0x7c, v6
	v_lshl_add_u64 v[8:9], v[8:9], 0, v[134:135]
	v_lshlrev_b32_e32 v134, 1, v7
	v_lshl_add_u64 v[8:9], v[8:9], 0, v[134:135]
	v_lshl_add_u64 v[196:197], v[194:195], 0, v[188:189]
	global_store_dwordx4 v[196:197], v[182:185], off

.LBB0_1153:
	ds_read_b128 v[146:149], v153
	ds_read_b128 v[158:161], v153 offset:1024
	ds_read_b128 v[162:165], v153 offset:2048
	ds_read_b128 v[166:169], v153 offset:3072
	s_add_u32 s54, s52, 0xfff80080
	s_addc_u32 s55, s53, -1
	s_cmp_eq_u32 s80, 28
	s_cselect_b32 s55, s45, s55
	s_cselect_b32 s54, s51, s54
	s_cselect_b32 s83, s76, s79
	s_cselect_b32 s82, s77, s78
	v_lshl_add_u64 v[202:203], s[52:53], 0, v[136:137]
	s_add_i32 m0, s61, 0xc000
	ds_read_b128 v[170:173], v154
	ds_read_b128 v[174:177], v154 offset:1024
	ds_read_b128 v[178:181], v154 offset:2048
	ds_read_b128 v[182:185], v154 offset:3072
	ds_read_b128 v[186:189], v154 offset:4096
	ds_read_b128 v[190:193], v154 offset:5120
	ds_read_b128 v[194:197], v154 offset:6144
	ds_read_b128 v[198:201], v154 offset:7168
	global_load_lds_dwordx4 v[202:203], off
	v_lshl_add_u64 v[202:203], s[52:53], 0, v[138:139]
	s_add_i32 m0, s61, 0xe000
	s_nop 0
	global_load_lds_dwordx4 v[202:203], off
	s_waitcnt lgkmcnt(8)
	s_barrier
	s_waitcnt lgkmcnt(0)
	s_setprio 1
	s_waitcnt lgkmcnt(0)
	v_mfma_f32_16x16x32_bf16 v[124:127], v[146:149], v[170:173], v[124:127]
	v_mfma_f32_16x16x32_bf16 v[120:123], v[162:165], v[170:173], v[120:123]
	v_mfma_f32_16x16x32_bf16 v[108:111], v[146:149], v[178:181], v[108:111]
	v_mfma_f32_16x16x32_bf16 v[104:107], v[162:165], v[178:181], v[104:107]
	v_mfma_f32_16x16x32_bf16 v[92:95], v[146:149], v[186:189], v[92:95]
	v_mfma_f32_16x16x32_bf16 v[88:91], v[162:165], v[186:189], v[88:91]
	v_mfma_f32_16x16x32_bf16 v[76:79], v[146:149], v[194:197], v[76:79]
	v_mfma_f32_16x16x32_bf16 v[72:75], v[162:165], v[194:197], v[72:75]
	v_mfma_f32_16x16x32_bf16 v[124:127], v[158:161], v[174:177], v[124:127]
	v_mfma_f32_16x16x32_bf16 v[120:123], v[166:169], v[174:177], v[120:123]
	v_mfma_f32_16x16x32_bf16 v[108:111], v[158:161], v[182:185], v[108:111]
	v_mfma_f32_16x16x32_bf16 v[104:107], v[166:169], v[182:185], v[104:107]
	v_mfma_f32_16x16x32_bf16 v[92:95], v[158:161], v[190:193], v[92:95]
	v_mfma_f32_16x16x32_bf16 v[88:91], v[166:169], v[190:193], v[88:91]
	v_mfma_f32_16x16x32_bf16 v[76:79], v[158:161], v[198:201], v[76:79]
	v_mfma_f32_16x16x32_bf16 v[72:75], v[166:169], v[198:201], v[72:75]
	s_setprio 0
	s_barrier
	s_add_i32 s81, s70, s60
	v_lshl_add_u64 v[218:219], s[82:83], 0, v[128:129]
	s_mov_b32 m0, s81
	ds_read_b128 v[202:205], v155
	ds_read_b128 v[206:209], v155 offset:1024
	ds_read_b128 v[210:213], v155 offset:2048
	ds_read_b128 v[214:217], v155 offset:3072
	global_load_lds_dwordx4 v[218:219], off
	v_lshl_add_u64 v[220:221], v[218:219], 0, s[12:13]
	s_add_i32 m0, s81, 0x2000
	s_nop 0
	global_load_lds_dwordx4 v[220:221], off
	s_barrier
	s_waitcnt lgkmcnt(0)
	s_setprio 1
	s_waitcnt lgkmcnt(0)
	v_mfma_f32_16x16x32_bf16 v[116:119], v[202:205], v[170:173], v[116:119]
	v_mfma_f32_16x16x32_bf16 v[112:115], v[210:213], v[170:173], v[112:115]
	v_mfma_f32_16x16x32_bf16 v[100:103], v[202:205], v[178:181], v[100:103]
	v_mfma_f32_16x16x32_bf16 v[96:99], v[210:213], v[178:181], v[96:99]
	v_mfma_f32_16x16x32_bf16 v[84:87], v[202:205], v[186:189], v[84:87]
	v_mfma_f32_16x16x32_bf16 v[80:83], v[210:213], v[186:189], v[80:83]
	v_mfma_f32_16x16x32_bf16 v[68:71], v[202:205], v[194:197], v[68:71]
	v_mfma_f32_16x16x32_bf16 v[64:67], v[210:213], v[194:197], v[64:67]
	v_mfma_f32_16x16x32_bf16 v[116:119], v[206:209], v[174:177], v[116:119]
	v_mfma_f32_16x16x32_bf16 v[112:115], v[214:217], v[174:177], v[112:115]
	v_mfma_f32_16x16x32_bf16 v[100:103], v[206:209], v[182:185], v[100:103]
	v_mfma_f32_16x16x32_bf16 v[96:99], v[214:217], v[182:185], v[96:99]
	v_mfma_f32_16x16x32_bf16 v[84:87], v[206:209], v[190:193], v[84:87]
	v_mfma_f32_16x16x32_bf16 v[80:83], v[214:217], v[190:193], v[80:83]
	v_mfma_f32_16x16x32_bf16 v[68:71], v[206:209], v[198:201], v[68:71]
	v_mfma_f32_16x16x32_bf16 v[64:67], v[214:217], v[198:201], v[64:67]
	s_setprio 0
	s_mov_b32 m0, s61
	v_lshl_add_u64 v[220:221], s[54:55], 0, v[130:131]
	s_barrier
	ds_read_b128 v[170:173], v154 offset:16384
	ds_read_b128 v[174:177], v154 offset:17408
	ds_read_b128 v[178:181], v154 offset:18432
	ds_read_b128 v[182:185], v154 offset:19456
	ds_read_b128 v[186:189], v154 offset:20480
	ds_read_b128 v[190:193], v154 offset:21504
	ds_read_b128 v[194:197], v154 offset:22528
	ds_read_b128 v[198:201], v154 offset:23552
	global_load_lds_dwordx4 v[220:221], off
	v_lshl_add_u64 v[222:223], s[54:55], 0, v[132:133]
	s_mov_b32 m0, s62
	s_nop 0
	global_load_lds_dwordx4 v[222:223], off
	s_barrier
	s_waitcnt lgkmcnt(0)
	s_setprio 1
	s_waitcnt lgkmcnt(0)
	v_mfma_f32_16x16x32_bf16 v[60:63], v[146:149], v[170:173], v[60:63]
	v_mfma_f32_16x16x32_bf16 v[56:59], v[162:165], v[170:173], v[56:59]
	v_mfma_f32_16x16x32_bf16 v[44:47], v[146:149], v[178:181], v[44:47]
	v_mfma_f32_16x16x32_bf16 v[40:43], v[162:165], v[178:181], v[40:43]
	v_mfma_f32_16x16x32_bf16 v[28:31], v[146:149], v[186:189], v[28:31]
	v_mfma_f32_16x16x32_bf16 v[24:27], v[162:165], v[186:189], v[24:27]
	v_mfma_f32_16x16x32_bf16 v[12:15], v[146:149], v[194:197], v[12:15]
	v_mfma_f32_16x16x32_bf16 v[8:11], v[162:165], v[194:197], v[8:11]
	v_mfma_f32_16x16x32_bf16 v[60:63], v[158:161], v[174:177], v[60:63]
	v_mfma_f32_16x16x32_bf16 v[56:59], v[166:169], v[174:177], v[56:59]
	v_mfma_f32_16x16x32_bf16 v[44:47], v[158:161], v[182:185], v[44:47]
	v_mfma_f32_16x16x32_bf16 v[40:43], v[166:169], v[182:185], v[40:43]
	v_mfma_f32_16x16x32_bf16 v[28:31], v[158:161], v[190:193], v[28:31]
	v_mfma_f32_16x16x32_bf16 v[24:27], v[166:169], v[190:193], v[24:27]
	v_mfma_f32_16x16x32_bf16 v[12:15], v[158:161], v[198:201], v[12:15]
	v_mfma_f32_16x16x32_bf16 v[8:11], v[166:169], v[198:201], v[8:11]
	s_setprio 0
	s_barrier
	s_add_i32 s81, s71, s60
	v_lshl_add_u64 v[146:147], v[218:219], 0, s[14:15]
	s_mov_b32 m0, s81
	s_nop 0
	global_load_lds_dwordx4 v[146:147], off
	v_lshl_add_u64 v[146:147], v[218:219], 0, s[18:19]
	s_add_i32 m0, s81, 0x2000
	s_nop 0
	global_load_lds_dwordx4 v[146:147], off
	s_waitcnt vmcnt(6)
	s_barrier
	s_setprio 1
	v_mfma_f32_16x16x32_bf16 v[52:55], v[202:205], v[170:173], v[52:55]
	v_mfma_f32_16x16x32_bf16 v[48:51], v[210:213], v[170:173], v[48:51]
	v_mfma_f32_16x16x32_bf16 v[36:39], v[202:205], v[178:181], v[36:39]
	v_mfma_f32_16x16x32_bf16 v[32:35], v[210:213], v[178:181], v[32:35]
	v_mfma_f32_16x16x32_bf16 v[20:23], v[202:205], v[186:189], v[20:23]
	v_mfma_f32_16x16x32_bf16 v[16:19], v[210:213], v[186:189], v[16:19]
	v_mfma_f32_16x16x32_bf16 v[4:7], v[202:205], v[194:197], v[4:7]
	v_mfma_f32_16x16x32_bf16 v[0:3], v[210:213], v[194:197], v[0:3]
	v_mfma_f32_16x16x32_bf16 v[52:55], v[206:209], v[174:177], v[52:55]
	v_mfma_f32_16x16x32_bf16 v[48:51], v[214:217], v[174:177], v[48:51]
	v_mfma_f32_16x16x32_bf16 v[36:39], v[206:209], v[182:185], v[36:39]
	v_mfma_f32_16x16x32_bf16 v[32:35], v[214:217], v[182:185], v[32:35]
	v_mfma_f32_16x16x32_bf16 v[20:23], v[206:209], v[190:193], v[20:23]
	v_mfma_f32_16x16x32_bf16 v[16:19], v[214:217], v[190:193], v[16:19]
	v_mfma_f32_16x16x32_bf16 v[4:7], v[206:209], v[198:201], v[4:7]
	v_mfma_f32_16x16x32_bf16 v[0:3], v[214:217], v[198:201], v[0:3]
	s_setprio 0
	s_add_i32 s81, 0, 0x18000
	v_add_u32_e32 v134, s81, v151
	s_barrier
	ds_read_b128 v[146:149], v134
	ds_read_b128 v[158:161], v134 offset:1024
	ds_read_b128 v[162:165], v134 offset:2048
	ds_read_b128 v[166:169], v134 offset:3072
	s_add_u32 s54, s54, 0x80000
	s_addc_u32 s55, s55, 0
	s_mov_b32 m0, s63
	v_lshl_add_u64 v[202:203], s[54:55], 0, v[130:131]
	ds_read_b128 v[170:173], v154 offset:32768
	ds_read_b128 v[174:177], v154 offset:33792
	ds_read_b128 v[178:181], v154 offset:34816
	ds_read_b128 v[182:185], v154 offset:35840
	ds_read_b128 v[186:189], v154 offset:36864
	ds_read_b128 v[190:193], v154 offset:37888
	ds_read_b128 v[194:197], v154 offset:38912
	ds_read_b128 v[198:201], v154 offset:39936
	global_load_lds_dwordx4 v[202:203], off
	v_lshl_add_u64 v[202:203], s[54:55], 0, v[132:133]
	s_mov_b32 m0, s64
	s_nop 0
	global_load_lds_dwordx4 v[202:203], off
	s_waitcnt lgkmcnt(8)
	s_barrier
	s_waitcnt lgkmcnt(0)
	s_setprio 1
	s_waitcnt lgkmcnt(0)
	v_mfma_f32_16x16x32_bf16 v[124:127], v[146:149], v[170:173], v[124:127]
	v_mfma_f32_16x16x32_bf16 v[120:123], v[162:165], v[170:173], v[120:123]
	v_mfma_f32_16x16x32_bf16 v[108:111], v[146:149], v[178:181], v[108:111]
	v_mfma_f32_16x16x32_bf16 v[104:107], v[162:165], v[178:181], v[104:107]
	v_mfma_f32_16x16x32_bf16 v[92:95], v[146:149], v[186:189], v[92:95]
	v_mfma_f32_16x16x32_bf16 v[88:91], v[162:165], v[186:189], v[88:91]
	v_mfma_f32_16x16x32_bf16 v[76:79], v[146:149], v[194:197], v[76:79]
	v_mfma_f32_16x16x32_bf16 v[72:75], v[162:165], v[194:197], v[72:75]
	v_mfma_f32_16x16x32_bf16 v[124:127], v[158:161], v[174:177], v[124:127]
	v_mfma_f32_16x16x32_bf16 v[120:123], v[166:169], v[174:177], v[120:123]
	v_mfma_f32_16x16x32_bf16 v[108:111], v[158:161], v[182:185], v[108:111]
	v_mfma_f32_16x16x32_bf16 v[104:107], v[166:169], v[182:185], v[104:107]
	v_mfma_f32_16x16x32_bf16 v[92:95], v[158:161], v[190:193], v[92:95]
	v_mfma_f32_16x16x32_bf16 v[88:91], v[166:169], v[190:193], v[88:91]
	v_mfma_f32_16x16x32_bf16 v[76:79], v[158:161], v[198:201], v[76:79]
	v_mfma_f32_16x16x32_bf16 v[72:75], v[166:169], v[198:201], v[72:75]
	s_setprio 0
	s_barrier
	s_add_i32 s54, 0, 0x1c000
	s_add_i32 s55, s81, s60
	v_add_u32_e32 v134, s54, v151
	v_lshl_add_u64 v[224:225], v[218:219], 0, s[26:27]
	s_mov_b32 m0, s55
	ds_read_b128 v[202:205], v134
	ds_read_b128 v[206:209], v134 offset:1024
	ds_read_b128 v[210:213], v134 offset:2048
	ds_read_b128 v[214:217], v134 offset:3072
	global_load_lds_dwordx4 v[224:225], off
	v_lshl_add_u64 v[224:225], v[218:219], 0, s[28:29]
	s_add_i32 m0, s55, 0x2000
	s_nop 0
	global_load_lds_dwordx4 v[224:225], off
	s_barrier
	s_waitcnt lgkmcnt(0)
	s_setprio 1
	s_waitcnt lgkmcnt(0)
	v_mfma_f32_16x16x32_bf16 v[116:119], v[202:205], v[170:173], v[116:119]
	v_mfma_f32_16x16x32_bf16 v[112:115], v[210:213], v[170:173], v[112:115]
	v_mfma_f32_16x16x32_bf16 v[100:103], v[202:205], v[178:181], v[100:103]
	v_mfma_f32_16x16x32_bf16 v[96:99], v[210:213], v[178:181], v[96:99]
	v_mfma_f32_16x16x32_bf16 v[84:87], v[202:205], v[186:189], v[84:87]
	v_mfma_f32_16x16x32_bf16 v[80:83], v[210:213], v[186:189], v[80:83]
	v_mfma_f32_16x16x32_bf16 v[68:71], v[202:205], v[194:197], v[68:71]
	v_mfma_f32_16x16x32_bf16 v[64:67], v[210:213], v[194:197], v[64:67]
	v_mfma_f32_16x16x32_bf16 v[116:119], v[206:209], v[174:177], v[116:119]
	v_mfma_f32_16x16x32_bf16 v[112:115], v[214:217], v[174:177], v[112:115]
	v_mfma_f32_16x16x32_bf16 v[100:103], v[206:209], v[182:185], v[100:103]
	v_mfma_f32_16x16x32_bf16 v[96:99], v[214:217], v[182:185], v[96:99]
	v_mfma_f32_16x16x32_bf16 v[84:87], v[206:209], v[190:193], v[84:87]
	v_mfma_f32_16x16x32_bf16 v[80:83], v[214:217], v[190:193], v[80:83]
	v_mfma_f32_16x16x32_bf16 v[68:71], v[206:209], v[198:201], v[68:71]
	v_mfma_f32_16x16x32_bf16 v[64:67], v[214:217], v[198:201], v[64:67]
	s_setprio 0
	s_mov_b32 m0, s66
	v_lshl_add_u64 v[220:221], v[220:221], 0, s[30:31]
	s_barrier
	ds_read_b128 v[170:173], v154 offset:49152
	ds_read_b128 v[174:177], v154 offset:50176
	ds_read_b128 v[178:181], v154 offset:51200
	ds_read_b128 v[182:185], v154 offset:52224
	ds_read_b128 v[186:189], v154 offset:53248
	ds_read_b128 v[190:193], v154 offset:54272
	ds_read_b128 v[194:197], v154 offset:55296
	ds_read_b128 v[198:201], v154 offset:56320
	global_load_lds_dwordx4 v[220:221], off
	v_lshl_add_u64 v[220:221], v[222:223], 0, s[30:31]
	s_mov_b32 m0, s67
	s_nop 0
	global_load_lds_dwordx4 v[220:221], off
	s_barrier
	s_waitcnt lgkmcnt(0)
	s_setprio 1
	s_waitcnt lgkmcnt(0)
	v_mfma_f32_16x16x32_bf16 v[60:63], v[146:149], v[170:173], v[60:63]
	v_mfma_f32_16x16x32_bf16 v[56:59], v[162:165], v[170:173], v[56:59]
	v_mfma_f32_16x16x32_bf16 v[44:47], v[146:149], v[178:181], v[44:47]
	v_mfma_f32_16x16x32_bf16 v[40:43], v[162:165], v[178:181], v[40:43]
	v_mfma_f32_16x16x32_bf16 v[28:31], v[146:149], v[186:189], v[28:31]
	v_mfma_f32_16x16x32_bf16 v[24:27], v[162:165], v[186:189], v[24:27]
	v_mfma_f32_16x16x32_bf16 v[12:15], v[146:149], v[194:197], v[12:15]
	v_mfma_f32_16x16x32_bf16 v[8:11], v[162:165], v[194:197], v[8:11]
	v_mfma_f32_16x16x32_bf16 v[60:63], v[158:161], v[174:177], v[60:63]
	v_mfma_f32_16x16x32_bf16 v[56:59], v[166:169], v[174:177], v[56:59]
	v_mfma_f32_16x16x32_bf16 v[44:47], v[158:161], v[182:185], v[44:47]
	v_mfma_f32_16x16x32_bf16 v[40:43], v[166:169], v[182:185], v[40:43]
	v_mfma_f32_16x16x32_bf16 v[28:31], v[158:161], v[190:193], v[28:31]
	v_mfma_f32_16x16x32_bf16 v[24:27], v[166:169], v[190:193], v[24:27]
	v_mfma_f32_16x16x32_bf16 v[12:15], v[158:161], v[198:201], v[12:15]
	v_mfma_f32_16x16x32_bf16 v[8:11], v[166:169], v[198:201], v[8:11]
	s_setprio 0
	s_barrier
	s_add_i32 s54, s54, s60
	v_lshl_add_u64 v[146:147], v[218:219], 0, s[34:35]
	s_mov_b32 m0, s54
	s_nop 0
	global_load_lds_dwordx4 v[146:147], off
	v_lshl_add_u64 v[146:147], v[218:219], 0, s[38:39]
	s_add_i32 m0, s54, 0x2000
	s_nop 0
	global_load_lds_dwordx4 v[146:147], off
	s_waitcnt vmcnt(6)
	s_barrier
	s_setprio 1
	v_mfma_f32_16x16x32_bf16 v[52:55], v[202:205], v[170:173], v[52:55]
	v_mfma_f32_16x16x32_bf16 v[48:51], v[210:213], v[170:173], v[48:51]
	v_mfma_f32_16x16x32_bf16 v[36:39], v[202:205], v[178:181], v[36:39]
	v_mfma_f32_16x16x32_bf16 v[32:35], v[210:213], v[178:181], v[32:35]
	v_mfma_f32_16x16x32_bf16 v[20:23], v[202:205], v[186:189], v[20:23]
	v_mfma_f32_16x16x32_bf16 v[16:19], v[210:213], v[186:189], v[16:19]
	v_mfma_f32_16x16x32_bf16 v[4:7], v[202:205], v[194:197], v[4:7]
	v_mfma_f32_16x16x32_bf16 v[0:3], v[210:213], v[194:197], v[0:3]
	v_mfma_f32_16x16x32_bf16 v[52:55], v[206:209], v[174:177], v[52:55]
	v_mfma_f32_16x16x32_bf16 v[48:51], v[214:217], v[174:177], v[48:51]
	v_mfma_f32_16x16x32_bf16 v[36:39], v[206:209], v[182:185], v[36:39]
	v_mfma_f32_16x16x32_bf16 v[32:35], v[214:217], v[182:185], v[32:35]
	v_mfma_f32_16x16x32_bf16 v[20:23], v[206:209], v[190:193], v[20:23]
	v_mfma_f32_16x16x32_bf16 v[16:19], v[214:217], v[190:193], v[16:19]
	v_mfma_f32_16x16x32_bf16 v[4:7], v[206:209], v[198:201], v[4:7]
	v_mfma_f32_16x16x32_bf16 v[0:3], v[214:217], v[198:201], v[0:3]
	s_setprio 0
	s_add_i32 s80, s80, 2
	s_add_u32 s78, s78, 0x8000
	s_addc_u32 s79, s79, 0
	s_add_u32 s52, s52, 0x100
	s_addc_u32 s53, s53, 0
	s_cmp_gt_u32 s80, 29
	s_barrier
	s_cbranch_scc0 .LBB0_1153
	s_lshl_b32 s45, s50, 21
	s_add_u32 s86, s20, s45
	s_addc_u32 s87, s21, 0
	s_add_u32 s84, s8, s45
	s_addc_u32 s85, s9, 0
	s_cmp_eq_u32 s50, 64
	s_cselect_b32 s84, s10, s84
	s_cselect_b32 s85, s11, s85
	s_lshl_b32 s45, s50, 20
	s_add_u32 s52, s22, s45
	s_addc_u32 s53, s23, 0
	v_and_b32_e32 v134, 8, v150
	v_and_b32_e32 v146, 0xfff7, v150
	v_lshl_add_u32 v147, v134, 1, v152
	s_lshl_b32 s45, s75, 8
	v_cmp_ne_u32_e32 vcc, 0, v134
	v_add_u32_e32 v147, s45, v147
	v_lshlrev_b32_e32 v146, 13, v146
	v_lshl_add_u32 v146, v147, 2, v146
	s_lshl_b32 s51, s50, 10
	s_cmp_eq_u32 s50, 64
	s_cselect_b32 s45, 1, 0
	s_add_u32 s50, s24, s51
	s_addc_u32 s51, s25, 0
	s_cmp_eq_u32 s45, 1
	s_cbranch_scc1 .Lepo_tail
	v_mov_b32_e32 v166, v146
	v_add_u32_e32 v167, 0x10000, v146
	global_load_dwordx4 v[170:173], v166, s[84:85]
	global_load_dwordx4 v[174:177], v167, s[84:85]
	global_load_dwordx4 v[178:181], v166, s[84:85] offset:512
	global_load_dwordx4 v[182:185], v167, s[84:85] offset:512
	v_add_u32_e32 v166, 0x20000, v146
	v_add_u32_e32 v167, 0x30000, v146
	global_load_dwordx4 v[186:189], v166, s[84:85]
	global_load_dwordx4 v[190:193], v167, s[84:85]
	global_load_dwordx4 v[194:197], v166, s[84:85] offset:512
	global_load_dwordx4 v[198:201], v167, s[84:85] offset:512
	v_add_u32_e32 v166, 0x40000, v146
	v_add_u32_e32 v167, 0x50000, v146
	global_load_dwordx4 v[202:205], v166, s[84:85]
	global_load_dwordx4 v[206:209], v167, s[84:85]
	global_load_dwordx4 v[210:213], v166, s[84:85] offset:512
	global_load_dwordx4 v[214:217], v167, s[84:85] offset:512
	v_mov_b32_e32 v158, v120
	v_mov_b32_e32 v159, v121
	v_mov_b32_e32 v160, v122
	v_mov_b32_e32 v161, v123
	v_mov_b32_e32 v162, v112
	v_mov_b32_e32 v163, v113
	v_mov_b32_e32 v164, v114
	v_mov_b32_e32 v165, v115
	v_mov_b32_dpp v120, v124 row_ror:8 row_mask:0xf bank_mask:0x3
	v_mov_b32_dpp v121, v125 row_ror:8 row_mask:0xf bank_mask:0x3
	v_mov_b32_dpp v122, v126 row_ror:8 row_mask:0xf bank_mask:0x3
	v_mov_b32_dpp v123, v127 row_ror:8 row_mask:0xf bank_mask:0x3
	v_mov_b32_dpp v112, v116 row_ror:8 row_mask:0xf bank_mask:0x3
	v_mov_b32_dpp v113, v117 row_ror:8 row_mask:0xf bank_mask:0x3
	v_mov_b32_dpp v114, v118 row_ror:8 row_mask:0xf bank_mask:0x3
	v_mov_b32_dpp v115, v119 row_ror:8 row_mask:0xf bank_mask:0x3
	v_mov_b32_dpp v124, v158 row_ror:8 row_mask:0xf bank_mask:0xc
	v_mov_b32_dpp v125, v159 row_ror:8 row_mask:0xf bank_mask:0xc
	v_mov_b32_dpp v126, v160 row_ror:8 row_mask:0xf bank_mask:0xc
	v_mov_b32_dpp v127, v161 row_ror:8 row_mask:0xf bank_mask:0xc
	v_mov_b32_dpp v116, v162 row_ror:8 row_mask:0xf bank_mask:0xc
	v_mov_b32_dpp v117, v163 row_ror:8 row_mask:0xf bank_mask:0xc
	v_mov_b32_dpp v118, v164 row_ror:8 row_mask:0xf bank_mask:0xc
	v_mov_b32_dpp v119, v165 row_ror:8 row_mask:0xf bank_mask:0xc
	v_mov_b32_e32 v166, v146
	v_add_u32_e32 v167, 0x10000, v146
	v_lshrrev_b32_e32 v168, 1, v166
	v_lshrrev_b32_e32 v169, 1, v167
	s_waitcnt vmcnt(8)
	v_pk_add_f32 v[124:125], v[124:125], v[170:171]
	v_pk_add_f32 v[126:127], v[126:127], v[172:173]
	v_pk_add_f32 v[120:121], v[120:121], v[174:175]
	v_pk_add_f32 v[122:123], v[122:123], v[176:177]
	v_pk_add_f32 v[116:117], v[116:117], v[178:179]
	v_pk_add_f32 v[118:119], v[118:119], v[180:181]
	v_pk_add_f32 v[112:113], v[112:113], v[182:183]
	v_pk_add_f32 v[114:115], v[114:115], v[184:185]
	global_store_dwordx4 v166, v[124:127], s[86:87]
	global_store_dwordx4 v167, v[120:123], s[86:87]
	global_store_dwordx4 v166, v[116:119], s[86:87] offset:512
	global_store_dwordx4 v167, v[112:115], s[86:87] offset:512
	v_cvt_pk_bf16_f32 v158, v124, v125
	v_cvt_pk_bf16_f32 v159, v126, v127
	v_cvt_pk_bf16_f32 v160, v120, v121
	v_cvt_pk_bf16_f32 v161, v122, v123
	v_cvt_pk_bf16_f32 v162, v116, v117
	v_cvt_pk_bf16_f32 v163, v118, v119
	v_cvt_pk_bf16_f32 v164, v112, v113
	v_cvt_pk_bf16_f32 v165, v114, v115
	global_store_dwordx2 v168, v[158:159], s[52:53]
	global_store_dwordx2 v169, v[160:161], s[52:53]
	global_store_dwordx2 v168, v[162:163], s[52:53] offset:256
	global_store_dwordx2 v169, v[164:165], s[52:53] offset:256
	v_mul_f32_e32 v148, v124, v124
	v_mul_f32_e32 v149, v120, v120
	v_fmac_f32_e32 v148, v125, v125
	v_fmac_f32_e32 v149, v121, v121
	v_fmac_f32_e32 v148, v126, v126
	v_fmac_f32_e32 v149, v122, v122
	v_fmac_f32_e32 v148, v127, v127
	v_fmac_f32_e32 v149, v123, v123
	v_fmac_f32_e32 v148, v116, v116
	v_fmac_f32_e32 v149, v112, v112
	v_fmac_f32_e32 v148, v117, v117
	v_fmac_f32_e32 v149, v113, v113
	v_fmac_f32_e32 v148, v118, v118
	v_fmac_f32_e32 v149, v114, v114
	v_fmac_f32_e32 v148, v119, v119
	v_fmac_f32_e32 v149, v115, v115
	s_nop 1
	v_add_f32_dpp v148, v148, v148 row_ror:8 row_mask:0xf bank_mask:0xf
	v_add_f32_dpp v149, v149, v149 row_ror:8 row_mask:0xf bank_mask:0xf
	v_mov_b32_e32 v134, v148
	v_mov_b32_e32 v147, v149
	s_nop 1
	v_permlane16_swap_b32_e32 v148, v134
	v_permlane16_swap_b32_e32 v149, v147
	v_add_f32_e32 v148, v148, v134
	v_add_f32_e32 v149, v149, v147
	v_mov_b32_e32 v134, v148
	v_mov_b32_e32 v147, v149
	s_nop 1
	v_permlane32_swap_b32_e32 v148, v134
	v_permlane32_swap_b32_e32 v149, v147
	v_add_f32_e32 v148, v148, v134
	v_add_f32_e32 v149, v149, v147
	v_cndmask_b32_e32 v148, v148, v149, vcc
	v_lshlrev_b32_e32 v134, 2, v150
	s_mov_b64 exec, s[4:5]
	global_atomic_add_f32 v134, v148, s[50:51]
	s_mov_b64 exec, -1
	v_add_u32_e32 v166, 0x60000, v146
	v_add_u32_e32 v167, 0x70000, v146
	global_load_dwordx4 v[170:173], v166, s[84:85]
	global_load_dwordx4 v[174:177], v167, s[84:85]
	global_load_dwordx4 v[178:181], v166, s[84:85] offset:512
	global_load_dwordx4 v[182:185], v167, s[84:85] offset:512
	v_mov_b32_e32 v158, v104
	v_mov_b32_e32 v159, v105
	v_mov_b32_e32 v160, v106
	v_mov_b32_e32 v161, v107
	v_mov_b32_e32 v162, v96
	v_mov_b32_e32 v163, v97
	v_mov_b32_e32 v164, v98
	v_mov_b32_e32 v165, v99
	v_mov_b32_dpp v104, v108 row_ror:8 row_mask:0xf bank_mask:0x3
	v_mov_b32_dpp v105, v109 row_ror:8 row_mask:0xf bank_mask:0x3
	v_mov_b32_dpp v106, v110 row_ror:8 row_mask:0xf bank_mask:0x3
	v_mov_b32_dpp v107, v111 row_ror:8 row_mask:0xf bank_mask:0x3
	v_mov_b32_dpp v96, v100 row_ror:8 row_mask:0xf bank_mask:0x3
	v_mov_b32_dpp v97, v101 row_ror:8 row_mask:0xf bank_mask:0x3
	v_mov_b32_dpp v98, v102 row_ror:8 row_mask:0xf bank_mask:0x3
	v_mov_b32_dpp v99, v103 row_ror:8 row_mask:0xf bank_mask:0x3
	v_mov_b32_dpp v108, v158 row_ror:8 row_mask:0xf bank_mask:0xc
	v_mov_b32_dpp v109, v159 row_ror:8 row_mask:0xf bank_mask:0xc
	v_mov_b32_dpp v110, v160 row_ror:8 row_mask:0xf bank_mask:0xc
	v_mov_b32_dpp v111, v161 row_ror:8 row_mask:0xf bank_mask:0xc
	v_mov_b32_dpp v100, v162 row_ror:8 row_mask:0xf bank_mask:0xc
	v_mov_b32_dpp v101, v163 row_ror:8 row_mask:0xf bank_mask:0xc
	v_mov_b32_dpp v102, v164 row_ror:8 row_mask:0xf bank_mask:0xc
	v_mov_b32_dpp v103, v165 row_ror:8 row_mask:0xf bank_mask:0xc
	v_add_u32_e32 v166, 0x20000, v146
	v_add_u32_e32 v167, 0x30000, v146
	v_lshrrev_b32_e32 v168, 1, v166
	v_lshrrev_b32_e32 v169, 1, v167
	s_waitcnt vmcnt(17)
	v_pk_add_f32 v[108:109], v[108:109], v[186:187]
	v_pk_add_f32 v[110:111], v[110:111], v[188:189]
	v_pk_add_f32 v[104:105], v[104:105], v[190:191]
	v_pk_add_f32 v[106:107], v[106:107], v[192:193]
	v_pk_add_f32 v[100:101], v[100:101], v[194:195]
	v_pk_add_f32 v[102:103], v[102:103], v[196:197]
	v_pk_add_f32 v[96:97], v[96:97], v[198:199]
	v_pk_add_f32 v[98:99], v[98:99], v[200:201]
	global_store_dwordx4 v166, v[108:111], s[86:87]
	global_store_dwordx4 v167, v[104:107], s[86:87]
	global_store_dwordx4 v166, v[100:103], s[86:87] offset:512
	global_store_dwordx4 v167, v[96:99], s[86:87] offset:512
	v_cvt_pk_bf16_f32 v158, v108, v109
	v_cvt_pk_bf16_f32 v159, v110, v111
	v_cvt_pk_bf16_f32 v160, v104, v105
	v_cvt_pk_bf16_f32 v161, v106, v107
	v_cvt_pk_bf16_f32 v162, v100, v101
	v_cvt_pk_bf16_f32 v163, v102, v103
	v_cvt_pk_bf16_f32 v164, v96, v97
	v_cvt_pk_bf16_f32 v165, v98, v99
	global_store_dwordx2 v168, v[158:159], s[52:53]
	global_store_dwordx2 v169, v[160:161], s[52:53]
	global_store_dwordx2 v168, v[162:163], s[52:53] offset:256
	global_store_dwordx2 v169, v[164:165], s[52:53] offset:256
	v_mul_f32_e32 v148, v108, v108
	v_mul_f32_e32 v149, v104, v104
	v_fmac_f32_e32 v148, v109, v109
	v_fmac_f32_e32 v149, v105, v105
	v_fmac_f32_e32 v148, v110, v110
	v_fmac_f32_e32 v149, v106, v106
	v_fmac_f32_e32 v148, v111, v111
	v_fmac_f32_e32 v149, v107, v107
	v_fmac_f32_e32 v148, v100, v100
	v_fmac_f32_e32 v149, v96, v96
	v_fmac_f32_e32 v148, v101, v101
	v_fmac_f32_e32 v149, v97, v97
	v_fmac_f32_e32 v148, v102, v102
	v_fmac_f32_e32 v149, v98, v98
	v_fmac_f32_e32 v148, v103, v103
	v_fmac_f32_e32 v149, v99, v99
	s_nop 1
	v_add_f32_dpp v148, v148, v148 row_ror:8 row_mask:0xf bank_mask:0xf
	v_add_f32_dpp v149, v149, v149 row_ror:8 row_mask:0xf bank_mask:0xf
	v_mov_b32_e32 v134, v148
	v_mov_b32_e32 v147, v149
	s_nop 1
	v_permlane16_swap_b32_e32 v148, v134
	v_permlane16_swap_b32_e32 v149, v147
	v_add_f32_e32 v148, v148, v134
	v_add_f32_e32 v149, v149, v147
	v_mov_b32_e32 v134, v148
	v_mov_b32_e32 v147, v149
	s_nop 1
	v_permlane32_swap_b32_e32 v148, v134
	v_permlane32_swap_b32_e32 v149, v147
	v_add_f32_e32 v148, v148, v134
	v_add_f32_e32 v149, v149, v147
	v_cndmask_b32_e32 v148, v148, v149, vcc
	v_lshlrev_b32_e32 v134, 2, v150
	s_mov_b64 exec, s[4:5]
	global_atomic_add_f32 v134, v148, s[50:51] offset:64
	s_mov_b64 exec, -1
	v_add_u32_e32 v166, 0x100000, v146
	v_add_u32_e32 v167, 0x110000, v146
	global_load_dwordx4 v[186:189], v166, s[84:85]
	global_load_dwordx4 v[190:193], v167, s[84:85]
	global_load_dwordx4 v[194:197], v166, s[84:85] offset:512
	global_load_dwordx4 v[198:201], v167, s[84:85] offset:512
	v_mov_b32_e32 v158, v88
	v_mov_b32_e32 v159, v89
	v_mov_b32_e32 v160, v90
	v_mov_b32_e32 v161, v91
	v_mov_b32_e32 v162, v80
	v_mov_b32_e32 v163, v81
	v_mov_b32_e32 v164, v82
	v_mov_b32_e32 v165, v83
	v_mov_b32_dpp v88, v92 row_ror:8 row_mask:0xf bank_mask:0x3
	v_mov_b32_dpp v89, v93 row_ror:8 row_mask:0xf bank_mask:0x3
	v_mov_b32_dpp v90, v94 row_ror:8 row_mask:0xf bank_mask:0x3
	v_mov_b32_dpp v91, v95 row_ror:8 row_mask:0xf bank_mask:0x3
	v_mov_b32_dpp v80, v84 row_ror:8 row_mask:0xf bank_mask:0x3
	v_mov_b32_dpp v81, v85 row_ror:8 row_mask:0xf bank_mask:0x3
	v_mov_b32_dpp v82, v86 row_ror:8 row_mask:0xf bank_mask:0x3
	v_mov_b32_dpp v83, v87 row_ror:8 row_mask:0xf bank_mask:0x3
	v_mov_b32_dpp v92, v158 row_ror:8 row_mask:0xf bank_mask:0xc
	v_mov_b32_dpp v93, v159 row_ror:8 row_mask:0xf bank_mask:0xc
	v_mov_b32_dpp v94, v160 row_ror:8 row_mask:0xf bank_mask:0xc
	v_mov_b32_dpp v95, v161 row_ror:8 row_mask:0xf bank_mask:0xc
	v_mov_b32_dpp v84, v162 row_ror:8 row_mask:0xf bank_mask:0xc
	v_mov_b32_dpp v85, v163 row_ror:8 row_mask:0xf bank_mask:0xc
	v_mov_b32_dpp v86, v164 row_ror:8 row_mask:0xf bank_mask:0xc
	v_mov_b32_dpp v87, v165 row_ror:8 row_mask:0xf bank_mask:0xc
	v_add_u32_e32 v166, 0x40000, v146
	v_add_u32_e32 v167, 0x50000, v146
	v_lshrrev_b32_e32 v168, 1, v166
	v_lshrrev_b32_e32 v169, 1, v167
	s_waitcnt vmcnt(26)
	v_pk_add_f32 v[92:93], v[92:93], v[202:203]
	v_pk_add_f32 v[94:95], v[94:95], v[204:205]
	v_pk_add_f32 v[88:89], v[88:89], v[206:207]
	v_pk_add_f32 v[90:91], v[90:91], v[208:209]
	v_pk_add_f32 v[84:85], v[84:85], v[210:211]
	v_pk_add_f32 v[86:87], v[86:87], v[212:213]
	v_pk_add_f32 v[80:81], v[80:81], v[214:215]
	v_pk_add_f32 v[82:83], v[82:83], v[216:217]
	global_store_dwordx4 v166, v[92:95], s[86:87]
	global_store_dwordx4 v167, v[88:91], s[86:87]
	global_store_dwordx4 v166, v[84:87], s[86:87] offset:512
	global_store_dwordx4 v167, v[80:83], s[86:87] offset:512
	v_cvt_pk_bf16_f32 v158, v92, v93
	v_cvt_pk_bf16_f32 v159, v94, v95
	v_cvt_pk_bf16_f32 v160, v88, v89
	v_cvt_pk_bf16_f32 v161, v90, v91
	v_cvt_pk_bf16_f32 v162, v84, v85
	v_cvt_pk_bf16_f32 v163, v86, v87
	v_cvt_pk_bf16_f32 v164, v80, v81
	v_cvt_pk_bf16_f32 v165, v82, v83
	global_store_dwordx2 v168, v[158:159], s[52:53]
	global_store_dwordx2 v169, v[160:161], s[52:53]
	global_store_dwordx2 v168, v[162:163], s[52:53] offset:256
	global_store_dwordx2 v169, v[164:165], s[52:53] offset:256
	v_mul_f32_e32 v148, v92, v92
	v_mul_f32_e32 v149, v88, v88
	v_fmac_f32_e32 v148, v93, v93
	v_fmac_f32_e32 v149, v89, v89
	v_fmac_f32_e32 v148, v94, v94
	v_fmac_f32_e32 v149, v90, v90
	v_fmac_f32_e32 v148, v95, v95
	v_fmac_f32_e32 v149, v91, v91
	v_fmac_f32_e32 v148, v84, v84
	v_fmac_f32_e32 v149, v80, v80
	v_fmac_f32_e32 v148, v85, v85
	v_fmac_f32_e32 v149, v81, v81
	v_fmac_f32_e32 v148, v86, v86
	v_fmac_f32_e32 v149, v82, v82
	v_fmac_f32_e32 v148, v87, v87
	v_fmac_f32_e32 v149, v83, v83
	s_nop 1
	v_add_f32_dpp v148, v148, v148 row_ror:8 row_mask:0xf bank_mask:0xf
	v_add_f32_dpp v149, v149, v149 row_ror:8 row_mask:0xf bank_mask:0xf
	v_mov_b32_e32 v134, v148
	v_mov_b32_e32 v147, v149
	s_nop 1
	v_permlane16_swap_b32_e32 v148, v134
	v_permlane16_swap_b32_e32 v149, v147
	v_add_f32_e32 v148, v148, v134
	v_add_f32_e32 v149, v149, v147
	v_mov_b32_e32 v134, v148
	v_mov_b32_e32 v147, v149
	s_nop 1
	v_permlane32_swap_b32_e32 v148, v134
	v_permlane32_swap_b32_e32 v149, v147
	v_add_f32_e32 v148, v148, v134
	v_add_f32_e32 v149, v149, v147
	v_cndmask_b32_e32 v148, v148, v149, vcc
	v_lshlrev_b32_e32 v134, 2, v150
	s_mov_b64 exec, s[4:5]
	global_atomic_add_f32 v134, v148, s[50:51] offset:128
	s_mov_b64 exec, -1
	v_add_u32_e32 v166, 0x120000, v146
	v_add_u32_e32 v167, 0x130000, v146
	global_load_dwordx4 v[202:205], v166, s[84:85]
	global_load_dwordx4 v[206:209], v167, s[84:85]
	global_load_dwordx4 v[210:213], v166, s[84:85] offset:512
	global_load_dwordx4 v[214:217], v167, s[84:85] offset:512
	v_mov_b32_e32 v158, v72
	v_mov_b32_e32 v159, v73
	v_mov_b32_e32 v160, v74
	v_mov_b32_e32 v161, v75
	v_mov_b32_e32 v162, v64
	v_mov_b32_e32 v163, v65
	v_mov_b32_e32 v164, v66
	v_mov_b32_e32 v165, v67
	v_mov_b32_dpp v72, v76 row_ror:8 row_mask:0xf bank_mask:0x3
	v_mov_b32_dpp v73, v77 row_ror:8 row_mask:0xf bank_mask:0x3
	v_mov_b32_dpp v74, v78 row_ror:8 row_mask:0xf bank_mask:0x3
	v_mov_b32_dpp v75, v79 row_ror:8 row_mask:0xf bank_mask:0x3
	v_mov_b32_dpp v64, v68 row_ror:8 row_mask:0xf bank_mask:0x3
	v_mov_b32_dpp v65, v69 row_ror:8 row_mask:0xf bank_mask:0x3
	v_mov_b32_dpp v66, v70 row_ror:8 row_mask:0xf bank_mask:0x3
	v_mov_b32_dpp v67, v71 row_ror:8 row_mask:0xf bank_mask:0x3
	v_mov_b32_dpp v76, v158 row_ror:8 row_mask:0xf bank_mask:0xc
	v_mov_b32_dpp v77, v159 row_ror:8 row_mask:0xf bank_mask:0xc
	v_mov_b32_dpp v78, v160 row_ror:8 row_mask:0xf bank_mask:0xc
	v_mov_b32_dpp v79, v161 row_ror:8 row_mask:0xf bank_mask:0xc
	v_mov_b32_dpp v68, v162 row_ror:8 row_mask:0xf bank_mask:0xc
	v_mov_b32_dpp v69, v163 row_ror:8 row_mask:0xf bank_mask:0xc
	v_mov_b32_dpp v70, v164 row_ror:8 row_mask:0xf bank_mask:0xc
	v_mov_b32_dpp v71, v165 row_ror:8 row_mask:0xf bank_mask:0xc
	v_add_u32_e32 v166, 0x60000, v146
	v_add_u32_e32 v167, 0x70000, v146
	v_lshrrev_b32_e32 v168, 1, v166
	v_lshrrev_b32_e32 v169, 1, v167
	s_waitcnt vmcnt(26)
	v_pk_add_f32 v[76:77], v[76:77], v[170:171]
	v_pk_add_f32 v[78:79], v[78:79], v[172:173]
	v_pk_add_f32 v[72:73], v[72:73], v[174:175]
	v_pk_add_f32 v[74:75], v[74:75], v[176:177]
	v_pk_add_f32 v[68:69], v[68:69], v[178:179]
	v_pk_add_f32 v[70:71], v[70:71], v[180:181]
	v_pk_add_f32 v[64:65], v[64:65], v[182:183]
	v_pk_add_f32 v[66:67], v[66:67], v[184:185]
	global_store_dwordx4 v166, v[76:79], s[86:87]
	global_store_dwordx4 v167, v[72:75], s[86:87]
	global_store_dwordx4 v166, v[68:71], s[86:87] offset:512
	global_store_dwordx4 v167, v[64:67], s[86:87] offset:512
	v_cvt_pk_bf16_f32 v158, v76, v77
	v_cvt_pk_bf16_f32 v159, v78, v79
	v_cvt_pk_bf16_f32 v160, v72, v73
	v_cvt_pk_bf16_f32 v161, v74, v75
	v_cvt_pk_bf16_f32 v162, v68, v69
	v_cvt_pk_bf16_f32 v163, v70, v71
	v_cvt_pk_bf16_f32 v164, v64, v65
	v_cvt_pk_bf16_f32 v165, v66, v67
	global_store_dwordx2 v168, v[158:159], s[52:53]
	global_store_dwordx2 v169, v[160:161], s[52:53]
	global_store_dwordx2 v168, v[162:163], s[52:53] offset:256
	global_store_dwordx2 v169, v[164:165], s[52:53] offset:256
	v_mul_f32_e32 v148, v76, v76
	v_mul_f32_e32 v149, v72, v72
	v_fmac_f32_e32 v148, v77, v77
	v_fmac_f32_e32 v149, v73, v73
	v_fmac_f32_e32 v148, v78, v78
	v_fmac_f32_e32 v149, v74, v74
	v_fmac_f32_e32 v148, v79, v79
	v_fmac_f32_e32 v149, v75, v75
	v_fmac_f32_e32 v148, v68, v68
	v_fmac_f32_e32 v149, v64, v64
	v_fmac_f32_e32 v148, v69, v69
	v_fmac_f32_e32 v149, v65, v65
	v_fmac_f32_e32 v148, v70, v70
	v_fmac_f32_e32 v149, v66, v66
	v_fmac_f32_e32 v148, v71, v71
	v_fmac_f32_e32 v149, v67, v67
	s_nop 1
	v_add_f32_dpp v148, v148, v148 row_ror:8 row_mask:0xf bank_mask:0xf
	v_add_f32_dpp v149, v149, v149 row_ror:8 row_mask:0xf bank_mask:0xf
	v_mov_b32_e32 v134, v148
	v_mov_b32_e32 v147, v149
	s_nop 1
	v_permlane16_swap_b32_e32 v148, v134
	v_permlane16_swap_b32_e32 v149, v147
	v_add_f32_e32 v148, v148, v134
	v_add_f32_e32 v149, v149, v147
	v_mov_b32_e32 v134, v148
	v_mov_b32_e32 v147, v149
	s_nop 1
	v_permlane32_swap_b32_e32 v148, v134
	v_permlane32_swap_b32_e32 v149, v147
	v_add_f32_e32 v148, v148, v134
	v_add_f32_e32 v149, v149, v147
	v_cndmask_b32_e32 v148, v148, v149, vcc
	v_lshlrev_b32_e32 v134, 2, v150
	s_mov_b64 exec, s[4:5]
	global_atomic_add_f32 v134, v148, s[50:51] offset:192
	s_mov_b64 exec, -1
	v_add_u32_e32 v166, 0x140000, v146
	v_add_u32_e32 v167, 0x150000, v146
	global_load_dwordx4 v[170:173], v166, s[84:85]
	global_load_dwordx4 v[174:177], v167, s[84:85]
	global_load_dwordx4 v[178:181], v166, s[84:85] offset:512
	global_load_dwordx4 v[182:185], v167, s[84:85] offset:512
	v_mov_b32_e32 v158, v56
	v_mov_b32_e32 v159, v57
	v_mov_b32_e32 v160, v58
	v_mov_b32_e32 v161, v59
	v_mov_b32_e32 v162, v48
	v_mov_b32_e32 v163, v49
	v_mov_b32_e32 v164, v50
	v_mov_b32_e32 v165, v51
	v_mov_b32_dpp v56, v60 row_ror:8 row_mask:0xf bank_mask:0x3
	v_mov_b32_dpp v57, v61 row_ror:8 row_mask:0xf bank_mask:0x3
	v_mov_b32_dpp v58, v62 row_ror:8 row_mask:0xf bank_mask:0x3
	v_mov_b32_dpp v59, v63 row_ror:8 row_mask:0xf bank_mask:0x3
	v_mov_b32_dpp v48, v52 row_ror:8 row_mask:0xf bank_mask:0x3
	v_mov_b32_dpp v49, v53 row_ror:8 row_mask:0xf bank_mask:0x3
	v_mov_b32_dpp v50, v54 row_ror:8 row_mask:0xf bank_mask:0x3
	v_mov_b32_dpp v51, v55 row_ror:8 row_mask:0xf bank_mask:0x3
	v_mov_b32_dpp v60, v158 row_ror:8 row_mask:0xf bank_mask:0xc
	v_mov_b32_dpp v61, v159 row_ror:8 row_mask:0xf bank_mask:0xc
	v_mov_b32_dpp v62, v160 row_ror:8 row_mask:0xf bank_mask:0xc
	v_mov_b32_dpp v63, v161 row_ror:8 row_mask:0xf bank_mask:0xc
	v_mov_b32_dpp v52, v162 row_ror:8 row_mask:0xf bank_mask:0xc
	v_mov_b32_dpp v53, v163 row_ror:8 row_mask:0xf bank_mask:0xc
	v_mov_b32_dpp v54, v164 row_ror:8 row_mask:0xf bank_mask:0xc
	v_mov_b32_dpp v55, v165 row_ror:8 row_mask:0xf bank_mask:0xc
	v_add_u32_e32 v166, 0x100000, v146
	v_add_u32_e32 v167, 0x110000, v146
	v_lshrrev_b32_e32 v168, 1, v166
	v_lshrrev_b32_e32 v169, 1, v167
	s_waitcnt vmcnt(26)
	v_pk_add_f32 v[60:61], v[60:61], v[186:187]
	v_pk_add_f32 v[62:63], v[62:63], v[188:189]
	v_pk_add_f32 v[56:57], v[56:57], v[190:191]
	v_pk_add_f32 v[58:59], v[58:59], v[192:193]
	v_pk_add_f32 v[52:53], v[52:53], v[194:195]
	v_pk_add_f32 v[54:55], v[54:55], v[196:197]
	v_pk_add_f32 v[48:49], v[48:49], v[198:199]
	v_pk_add_f32 v[50:51], v[50:51], v[200:201]
	global_store_dwordx4 v166, v[60:63], s[86:87]
	global_store_dwordx4 v167, v[56:59], s[86:87]
	global_store_dwordx4 v166, v[52:55], s[86:87] offset:512
	global_store_dwordx4 v167, v[48:51], s[86:87] offset:512
	v_cvt_pk_bf16_f32 v158, v60, v61
	v_cvt_pk_bf16_f32 v159, v62, v63
	v_cvt_pk_bf16_f32 v160, v56, v57
	v_cvt_pk_bf16_f32 v161, v58, v59
	v_cvt_pk_bf16_f32 v162, v52, v53
	v_cvt_pk_bf16_f32 v163, v54, v55
	v_cvt_pk_bf16_f32 v164, v48, v49
	v_cvt_pk_bf16_f32 v165, v50, v51
	global_store_dwordx2 v168, v[158:159], s[52:53]
	global_store_dwordx2 v169, v[160:161], s[52:53]
	global_store_dwordx2 v168, v[162:163], s[52:53] offset:256
	global_store_dwordx2 v169, v[164:165], s[52:53] offset:256
	v_mul_f32_e32 v148, v60, v60
	v_mul_f32_e32 v149, v56, v56
	v_fmac_f32_e32 v148, v61, v61
	v_fmac_f32_e32 v149, v57, v57
	v_fmac_f32_e32 v148, v62, v62
	v_fmac_f32_e32 v149, v58, v58
	v_fmac_f32_e32 v148, v63, v63
	v_fmac_f32_e32 v149, v59, v59
	v_fmac_f32_e32 v148, v52, v52
	v_fmac_f32_e32 v149, v48, v48
	v_fmac_f32_e32 v148, v53, v53
	v_fmac_f32_e32 v149, v49, v49
	v_fmac_f32_e32 v148, v54, v54
	v_fmac_f32_e32 v149, v50, v50
	v_fmac_f32_e32 v148, v55, v55
	v_fmac_f32_e32 v149, v51, v51
	s_nop 1
	v_add_f32_dpp v148, v148, v148 row_ror:8 row_mask:0xf bank_mask:0xf
	v_add_f32_dpp v149, v149, v149 row_ror:8 row_mask:0xf bank_mask:0xf
	v_mov_b32_e32 v134, v148
	v_mov_b32_e32 v147, v149
	s_nop 1
	v_permlane16_swap_b32_e32 v148, v134
	v_permlane16_swap_b32_e32 v149, v147
	v_add_f32_e32 v148, v148, v134
	v_add_f32_e32 v149, v149, v147
	v_mov_b32_e32 v134, v148
	v_mov_b32_e32 v147, v149
	s_nop 1
	v_permlane32_swap_b32_e32 v148, v134
	v_permlane32_swap_b32_e32 v149, v147
	v_add_f32_e32 v148, v148, v134
	v_add_f32_e32 v149, v149, v147
	v_cndmask_b32_e32 v148, v148, v149, vcc
	v_lshlrev_b32_e32 v134, 2, v150
	s_mov_b64 exec, s[4:5]
	global_atomic_add_f32 v134, v148, s[50:51] offset:512
	s_mov_b64 exec, -1
	v_add_u32_e32 v166, 0x160000, v146
	v_add_u32_e32 v167, 0x170000, v146
	global_load_dwordx4 v[186:189], v166, s[84:85]
	global_load_dwordx4 v[190:193], v167, s[84:85]
	global_load_dwordx4 v[194:197], v166, s[84:85] offset:512
	global_load_dwordx4 v[198:201], v167, s[84:85] offset:512
	v_mov_b32_e32 v158, v40
	v_mov_b32_e32 v159, v41
	v_mov_b32_e32 v160, v42
	v_mov_b32_e32 v161, v43
	v_mov_b32_e32 v162, v32
	v_mov_b32_e32 v163, v33
	v_mov_b32_e32 v164, v34
	v_mov_b32_e32 v165, v35
	v_mov_b32_dpp v40, v44 row_ror:8 row_mask:0xf bank_mask:0x3
	v_mov_b32_dpp v41, v45 row_ror:8 row_mask:0xf bank_mask:0x3
	v_mov_b32_dpp v42, v46 row_ror:8 row_mask:0xf bank_mask:0x3
	v_mov_b32_dpp v43, v47 row_ror:8 row_mask:0xf bank_mask:0x3
	v_mov_b32_dpp v32, v36 row_ror:8 row_mask:0xf bank_mask:0x3
	v_mov_b32_dpp v33, v37 row_ror:8 row_mask:0xf bank_mask:0x3
	v_mov_b32_dpp v34, v38 row_ror:8 row_mask:0xf bank_mask:0x3
	v_mov_b32_dpp v35, v39 row_ror:8 row_mask:0xf bank_mask:0x3
	v_mov_b32_dpp v44, v158 row_ror:8 row_mask:0xf bank_mask:0xc
	v_mov_b32_dpp v45, v159 row_ror:8 row_mask:0xf bank_mask:0xc
	v_mov_b32_dpp v46, v160 row_ror:8 row_mask:0xf bank_mask:0xc
	v_mov_b32_dpp v47, v161 row_ror:8 row_mask:0xf bank_mask:0xc
	v_mov_b32_dpp v36, v162 row_ror:8 row_mask:0xf bank_mask:0xc
	v_mov_b32_dpp v37, v163 row_ror:8 row_mask:0xf bank_mask:0xc
	v_mov_b32_dpp v38, v164 row_ror:8 row_mask:0xf bank_mask:0xc
	v_mov_b32_dpp v39, v165 row_ror:8 row_mask:0xf bank_mask:0xc
	v_add_u32_e32 v166, 0x120000, v146
	v_add_u32_e32 v167, 0x130000, v146
	v_lshrrev_b32_e32 v168, 1, v166
	v_lshrrev_b32_e32 v169, 1, v167
	s_waitcnt vmcnt(26)
	v_pk_add_f32 v[44:45], v[44:45], v[202:203]
	v_pk_add_f32 v[46:47], v[46:47], v[204:205]
	v_pk_add_f32 v[40:41], v[40:41], v[206:207]
	v_pk_add_f32 v[42:43], v[42:43], v[208:209]
	v_pk_add_f32 v[36:37], v[36:37], v[210:211]
	v_pk_add_f32 v[38:39], v[38:39], v[212:213]
	v_pk_add_f32 v[32:33], v[32:33], v[214:215]
	v_pk_add_f32 v[34:35], v[34:35], v[216:217]
	global_store_dwordx4 v166, v[44:47], s[86:87]
	global_store_dwordx4 v167, v[40:43], s[86:87]
	global_store_dwordx4 v166, v[36:39], s[86:87] offset:512
	global_store_dwordx4 v167, v[32:35], s[86:87] offset:512
	v_cvt_pk_bf16_f32 v158, v44, v45
	v_cvt_pk_bf16_f32 v159, v46, v47
	v_cvt_pk_bf16_f32 v160, v40, v41
	v_cvt_pk_bf16_f32 v161, v42, v43
	v_cvt_pk_bf16_f32 v162, v36, v37
	v_cvt_pk_bf16_f32 v163, v38, v39
	v_cvt_pk_bf16_f32 v164, v32, v33
	v_cvt_pk_bf16_f32 v165, v34, v35
	global_store_dwordx2 v168, v[158:159], s[52:53]
	global_store_dwordx2 v169, v[160:161], s[52:53]
	global_store_dwordx2 v168, v[162:163], s[52:53] offset:256
	global_store_dwordx2 v169, v[164:165], s[52:53] offset:256
	v_mul_f32_e32 v148, v44, v44
	v_mul_f32_e32 v149, v40, v40
	v_fmac_f32_e32 v148, v45, v45
	v_fmac_f32_e32 v149, v41, v41
	v_fmac_f32_e32 v148, v46, v46
	v_fmac_f32_e32 v149, v42, v42
	v_fmac_f32_e32 v148, v47, v47
	v_fmac_f32_e32 v149, v43, v43
	v_fmac_f32_e32 v148, v36, v36
	v_fmac_f32_e32 v149, v32, v32
	v_fmac_f32_e32 v148, v37, v37
	v_fmac_f32_e32 v149, v33, v33
	v_fmac_f32_e32 v148, v38, v38
	v_fmac_f32_e32 v149, v34, v34
	v_fmac_f32_e32 v148, v39, v39
	v_fmac_f32_e32 v149, v35, v35
	s_nop 1
	v_add_f32_dpp v148, v148, v148 row_ror:8 row_mask:0xf bank_mask:0xf
	v_add_f32_dpp v149, v149, v149 row_ror:8 row_mask:0xf bank_mask:0xf
	v_mov_b32_e32 v134, v148
	v_mov_b32_e32 v147, v149
	s_nop 1
	v_permlane16_swap_b32_e32 v148, v134
	v_permlane16_swap_b32_e32 v149, v147
	v_add_f32_e32 v148, v148, v134
	v_add_f32_e32 v149, v149, v147
	v_mov_b32_e32 v134, v148
	v_mov_b32_e32 v147, v149
	s_nop 1
	v_permlane32_swap_b32_e32 v148, v134
	v_permlane32_swap_b32_e32 v149, v147
	v_add_f32_e32 v148, v148, v134
	v_add_f32_e32 v149, v149, v147
	v_cndmask_b32_e32 v148, v148, v149, vcc
	v_lshlrev_b32_e32 v134, 2, v150
	s_mov_b64 exec, s[4:5]
	global_atomic_add_f32 v134, v148, s[50:51] offset:576
	s_mov_b64 exec, -1
	v_mov_b32_e32 v158, v24
	v_mov_b32_e32 v159, v25
	v_mov_b32_e32 v160, v26
	v_mov_b32_e32 v161, v27
	v_mov_b32_e32 v162, v16
	v_mov_b32_e32 v163, v17
	v_mov_b32_e32 v164, v18
	v_mov_b32_e32 v165, v19
	v_mov_b32_dpp v24, v28 row_ror:8 row_mask:0xf bank_mask:0x3
	v_mov_b32_dpp v25, v29 row_ror:8 row_mask:0xf bank_mask:0x3
	v_mov_b32_dpp v26, v30 row_ror:8 row_mask:0xf bank_mask:0x3
	v_mov_b32_dpp v27, v31 row_ror:8 row_mask:0xf bank_mask:0x3
	v_mov_b32_dpp v16, v20 row_ror:8 row_mask:0xf bank_mask:0x3
	v_mov_b32_dpp v17, v21 row_ror:8 row_mask:0xf bank_mask:0x3
	v_mov_b32_dpp v18, v22 row_ror:8 row_mask:0xf bank_mask:0x3
	v_mov_b32_dpp v19, v23 row_ror:8 row_mask:0xf bank_mask:0x3
	v_mov_b32_dpp v28, v158 row_ror:8 row_mask:0xf bank_mask:0xc
	v_mov_b32_dpp v29, v159 row_ror:8 row_mask:0xf bank_mask:0xc
	v_mov_b32_dpp v30, v160 row_ror:8 row_mask:0xf bank_mask:0xc
	v_mov_b32_dpp v31, v161 row_ror:8 row_mask:0xf bank_mask:0xc
	v_mov_b32_dpp v20, v162 row_ror:8 row_mask:0xf bank_mask:0xc
	v_mov_b32_dpp v21, v163 row_ror:8 row_mask:0xf bank_mask:0xc
	v_mov_b32_dpp v22, v164 row_ror:8 row_mask:0xf bank_mask:0xc
	v_mov_b32_dpp v23, v165 row_ror:8 row_mask:0xf bank_mask:0xc
	v_add_u32_e32 v166, 0x140000, v146
	v_add_u32_e32 v167, 0x150000, v146
	v_lshrrev_b32_e32 v168, 1, v166
	v_lshrrev_b32_e32 v169, 1, v167
	s_waitcnt vmcnt(22)
	v_pk_add_f32 v[28:29], v[28:29], v[170:171]
	v_pk_add_f32 v[30:31], v[30:31], v[172:173]
	v_pk_add_f32 v[24:25], v[24:25], v[174:175]
	v_pk_add_f32 v[26:27], v[26:27], v[176:177]
	v_pk_add_f32 v[20:21], v[20:21], v[178:179]
	v_pk_add_f32 v[22:23], v[22:23], v[180:181]
	v_pk_add_f32 v[16:17], v[16:17], v[182:183]
	v_pk_add_f32 v[18:19], v[18:19], v[184:185]
	global_store_dwordx4 v166, v[28:31], s[86:87]
	global_store_dwordx4 v167, v[24:27], s[86:87]
	global_store_dwordx4 v166, v[20:23], s[86:87] offset:512
	global_store_dwordx4 v167, v[16:19], s[86:87] offset:512
	v_cvt_pk_bf16_f32 v158, v28, v29
	v_cvt_pk_bf16_f32 v159, v30, v31
	v_cvt_pk_bf16_f32 v160, v24, v25
	v_cvt_pk_bf16_f32 v161, v26, v27
	v_cvt_pk_bf16_f32 v162, v20, v21
	v_cvt_pk_bf16_f32 v163, v22, v23
	v_cvt_pk_bf16_f32 v164, v16, v17
	v_cvt_pk_bf16_f32 v165, v18, v19
	global_store_dwordx2 v168, v[158:159], s[52:53]
	global_store_dwordx2 v169, v[160:161], s[52:53]
	global_store_dwordx2 v168, v[162:163], s[52:53] offset:256
	global_store_dwordx2 v169, v[164:165], s[52:53] offset:256
	v_mul_f32_e32 v148, v28, v28
	v_mul_f32_e32 v149, v24, v24
	v_fmac_f32_e32 v148, v29, v29
	v_fmac_f32_e32 v149, v25, v25
	v_fmac_f32_e32 v148, v30, v30
	v_fmac_f32_e32 v149, v26, v26
	v_fmac_f32_e32 v148, v31, v31
	v_fmac_f32_e32 v149, v27, v27
	v_fmac_f32_e32 v148, v20, v20
	v_fmac_f32_e32 v149, v16, v16
	v_fmac_f32_e32 v148, v21, v21
	v_fmac_f32_e32 v149, v17, v17
	v_fmac_f32_e32 v148, v22, v22
	v_fmac_f32_e32 v149, v18, v18
	v_fmac_f32_e32 v148, v23, v23
	v_fmac_f32_e32 v149, v19, v19
	s_nop 1
	v_add_f32_dpp v148, v148, v148 row_ror:8 row_mask:0xf bank_mask:0xf
	v_add_f32_dpp v149, v149, v149 row_ror:8 row_mask:0xf bank_mask:0xf
	v_mov_b32_e32 v134, v148
	v_mov_b32_e32 v147, v149
	s_nop 1
	v_permlane16_swap_b32_e32 v148, v134
	v_permlane16_swap_b32_e32 v149, v147
	v_add_f32_e32 v148, v148, v134
	v_add_f32_e32 v149, v149, v147
	v_mov_b32_e32 v134, v148
	v_mov_b32_e32 v147, v149
	s_nop 1
	v_permlane32_swap_b32_e32 v148, v134
	v_permlane32_swap_b32_e32 v149, v147
	v_add_f32_e32 v148, v148, v134
	v_add_f32_e32 v149, v149, v147
	v_cndmask_b32_e32 v148, v148, v149, vcc
	v_lshlrev_b32_e32 v134, 2, v150
	s_mov_b64 exec, s[4:5]
	global_atomic_add_f32 v134, v148, s[50:51] offset:640
	s_mov_b64 exec, -1
	v_mov_b32_e32 v158, v8
	v_mov_b32_e32 v159, v9
	v_mov_b32_e32 v160, v10
	v_mov_b32_e32 v161, v11
	v_mov_b32_e32 v162, v0
	v_mov_b32_e32 v163, v1
	v_mov_b32_e32 v164, v2
	v_mov_b32_e32 v165, v3
	v_mov_b32_dpp v8, v12 row_ror:8 row_mask:0xf bank_mask:0x3
	v_mov_b32_dpp v9, v13 row_ror:8 row_mask:0xf bank_mask:0x3
	v_mov_b32_dpp v10, v14 row_ror:8 row_mask:0xf bank_mask:0x3
	v_mov_b32_dpp v11, v15 row_ror:8 row_mask:0xf bank_mask:0x3
	v_mov_b32_dpp v0, v4 row_ror:8 row_mask:0xf bank_mask:0x3
	v_mov_b32_dpp v1, v5 row_ror:8 row_mask:0xf bank_mask:0x3
	v_mov_b32_dpp v2, v6 row_ror:8 row_mask:0xf bank_mask:0x3
	v_mov_b32_dpp v3, v7 row_ror:8 row_mask:0xf bank_mask:0x3
	v_mov_b32_dpp v12, v158 row_ror:8 row_mask:0xf bank_mask:0xc
	v_mov_b32_dpp v13, v159 row_ror:8 row_mask:0xf bank_mask:0xc
	v_mov_b32_dpp v14, v160 row_ror:8 row_mask:0xf bank_mask:0xc
	v_mov_b32_dpp v15, v161 row_ror:8 row_mask:0xf bank_mask:0xc
	v_mov_b32_dpp v4, v162 row_ror:8 row_mask:0xf bank_mask:0xc
	v_mov_b32_dpp v5, v163 row_ror:8 row_mask:0xf bank_mask:0xc
	v_mov_b32_dpp v6, v164 row_ror:8 row_mask:0xf bank_mask:0xc
	v_mov_b32_dpp v7, v165 row_ror:8 row_mask:0xf bank_mask:0xc
	v_add_u32_e32 v166, 0x160000, v146
	v_add_u32_e32 v167, 0x170000, v146
	v_lshrrev_b32_e32 v168, 1, v166
	v_lshrrev_b32_e32 v169, 1, v167
	s_waitcnt vmcnt(18)
	v_pk_add_f32 v[12:13], v[12:13], v[186:187]
	v_pk_add_f32 v[14:15], v[14:15], v[188:189]
	v_pk_add_f32 v[8:9], v[8:9], v[190:191]
	v_pk_add_f32 v[10:11], v[10:11], v[192:193]
	v_pk_add_f32 v[4:5], v[4:5], v[194:195]
	v_pk_add_f32 v[6:7], v[6:7], v[196:197]
	v_pk_add_f32 v[0:1], v[0:1], v[198:199]
	v_pk_add_f32 v[2:3], v[2:3], v[200:201]
	global_store_dwordx4 v166, v[12:15], s[86:87]
	global_store_dwordx4 v167, v[8:11], s[86:87]
	global_store_dwordx4 v166, v[4:7], s[86:87] offset:512
	global_store_dwordx4 v167, v[0:3], s[86:87] offset:512
	v_cvt_pk_bf16_f32 v158, v12, v13
	v_cvt_pk_bf16_f32 v159, v14, v15
	v_cvt_pk_bf16_f32 v160, v8, v9
	v_cvt_pk_bf16_f32 v161, v10, v11
	v_cvt_pk_bf16_f32 v162, v4, v5
	v_cvt_pk_bf16_f32 v163, v6, v7
	v_cvt_pk_bf16_f32 v164, v0, v1
	v_cvt_pk_bf16_f32 v165, v2, v3
	global_store_dwordx2 v168, v[158:159], s[52:53]
	global_store_dwordx2 v169, v[160:161], s[52:53]
	global_store_dwordx2 v168, v[162:163], s[52:53] offset:256
	global_store_dwordx2 v169, v[164:165], s[52:53] offset:256
	v_mul_f32_e32 v148, v12, v12
	v_mul_f32_e32 v149, v8, v8
	v_fmac_f32_e32 v148, v13, v13
	v_fmac_f32_e32 v149, v9, v9
	v_fmac_f32_e32 v148, v14, v14
	v_fmac_f32_e32 v149, v10, v10
	v_fmac_f32_e32 v148, v15, v15
	v_fmac_f32_e32 v149, v11, v11
	v_fmac_f32_e32 v148, v4, v4
	v_fmac_f32_e32 v149, v0, v0
	v_fmac_f32_e32 v148, v5, v5
	v_fmac_f32_e32 v149, v1, v1
	v_fmac_f32_e32 v148, v6, v6
	v_fmac_f32_e32 v149, v2, v2
	v_fmac_f32_e32 v148, v7, v7
	v_fmac_f32_e32 v149, v3, v3
	s_nop 1
	v_add_f32_dpp v148, v148, v148 row_ror:8 row_mask:0xf bank_mask:0xf
	v_add_f32_dpp v149, v149, v149 row_ror:8 row_mask:0xf bank_mask:0xf
	v_mov_b32_e32 v134, v148
	v_mov_b32_e32 v147, v149
	s_nop 1
	v_permlane16_swap_b32_e32 v148, v134
	v_permlane16_swap_b32_e32 v149, v147
	v_add_f32_e32 v148, v148, v134
	v_add_f32_e32 v149, v149, v147
	v_mov_b32_e32 v134, v148
	v_mov_b32_e32 v147, v149
	s_nop 1
	v_permlane32_swap_b32_e32 v148, v134
	v_permlane32_swap_b32_e32 v149, v147
	v_add_f32_e32 v148, v148, v134
	v_add_f32_e32 v149, v149, v147
	v_cndmask_b32_e32 v148, v148, v149, vcc
	v_lshlrev_b32_e32 v134, 2, v150
	s_mov_b64 exec, s[4:5]
	global_atomic_add_f32 v134, v148, s[50:51] offset:704
	s_mov_b64 exec, -1
	s_branch .LBB0_1142
.Lepo_tail:
	v_mov_b32_e32 v166, v146
	v_add_u32_e32 v167, 0x10000, v146
	global_load_dwordx4 v[170:173], v166, s[84:85]
	global_load_dwordx4 v[174:177], v167, s[84:85]
	global_load_dwordx4 v[178:181], v166, s[84:85] offset:512
	global_load_dwordx4 v[182:185], v167, s[84:85] offset:512
	v_add_u32_e32 v166, 0x20000, v146
	v_add_u32_e32 v167, 0x30000, v146
	global_load_dwordx4 v[186:189], v166, s[84:85]
	global_load_dwordx4 v[190:193], v167, s[84:85]
	global_load_dwordx4 v[194:197], v166, s[84:85] offset:512
	global_load_dwordx4 v[198:201], v167, s[84:85] offset:512
	v_add_u32_e32 v166, 0x40000, v146
	v_add_u32_e32 v167, 0x50000, v146
	global_load_dwordx4 v[202:205], v166, s[84:85]
	global_load_dwordx4 v[206:209], v167, s[84:85]
	global_load_dwordx4 v[210:213], v166, s[84:85] offset:512
	global_load_dwordx4 v[214:217], v167, s[84:85] offset:512
	v_mov_b32_e32 v158, v120
	v_mov_b32_e32 v159, v121
	v_mov_b32_e32 v160, v122
	v_mov_b32_e32 v161, v123
	v_mov_b32_e32 v162, v112
	v_mov_b32_e32 v163, v113
	v_mov_b32_e32 v164, v114
	v_mov_b32_e32 v165, v115
	v_mov_b32_dpp v120, v124 row_ror:8 row_mask:0xf bank_mask:0x3
	v_mov_b32_dpp v121, v125 row_ror:8 row_mask:0xf bank_mask:0x3
	v_mov_b32_dpp v122, v126 row_ror:8 row_mask:0xf bank_mask:0x3
	v_mov_b32_dpp v123, v127 row_ror:8 row_mask:0xf bank_mask:0x3
	v_mov_b32_dpp v112, v116 row_ror:8 row_mask:0xf bank_mask:0x3
	v_mov_b32_dpp v113, v117 row_ror:8 row_mask:0xf bank_mask:0x3
	v_mov_b32_dpp v114, v118 row_ror:8 row_mask:0xf bank_mask:0x3
	v_mov_b32_dpp v115, v119 row_ror:8 row_mask:0xf bank_mask:0x3
	v_mov_b32_dpp v124, v158 row_ror:8 row_mask:0xf bank_mask:0xc
	v_mov_b32_dpp v125, v159 row_ror:8 row_mask:0xf bank_mask:0xc
	v_mov_b32_dpp v126, v160 row_ror:8 row_mask:0xf bank_mask:0xc
	v_mov_b32_dpp v127, v161 row_ror:8 row_mask:0xf bank_mask:0xc
	v_mov_b32_dpp v116, v162 row_ror:8 row_mask:0xf bank_mask:0xc
	v_mov_b32_dpp v117, v163 row_ror:8 row_mask:0xf bank_mask:0xc
	v_mov_b32_dpp v118, v164 row_ror:8 row_mask:0xf bank_mask:0xc
	v_mov_b32_dpp v119, v165 row_ror:8 row_mask:0xf bank_mask:0xc
	v_mov_b32_e32 v166, v146
	v_add_u32_e32 v167, 0x10000, v146
	v_lshrrev_b32_e32 v168, 1, v166
	v_lshrrev_b32_e32 v169, 1, v167
	s_waitcnt vmcnt(8)
	v_pk_add_f32 v[124:125], v[124:125], v[170:171]
	v_pk_add_f32 v[126:127], v[126:127], v[172:173]
	v_pk_add_f32 v[120:121], v[120:121], v[174:175]
	v_pk_add_f32 v[122:123], v[122:123], v[176:177]
	v_pk_add_f32 v[116:117], v[116:117], v[178:179]
	v_pk_add_f32 v[118:119], v[118:119], v[180:181]
	v_pk_add_f32 v[112:113], v[112:113], v[182:183]
	v_pk_add_f32 v[114:115], v[114:115], v[184:185]
	global_store_dwordx4 v166, v[124:127], s[86:87]
	global_store_dwordx4 v167, v[120:123], s[86:87]
	global_store_dwordx4 v166, v[116:119], s[86:87] offset:512
	global_store_dwordx4 v167, v[112:115], s[86:87] offset:512
	v_cvt_pk_bf16_f32 v158, v124, v125
	v_cvt_pk_bf16_f32 v159, v126, v127
	v_cvt_pk_bf16_f32 v160, v120, v121
	v_cvt_pk_bf16_f32 v161, v122, v123
	v_cvt_pk_bf16_f32 v162, v116, v117
	v_cvt_pk_bf16_f32 v163, v118, v119
	v_cvt_pk_bf16_f32 v164, v112, v113
	v_cvt_pk_bf16_f32 v165, v114, v115
	global_store_dwordx2 v168, v[158:159], s[52:53]
	global_store_dwordx2 v169, v[160:161], s[52:53]
	global_store_dwordx2 v168, v[162:163], s[52:53] offset:256
	global_store_dwordx2 v169, v[164:165], s[52:53] offset:256
	v_mul_f32_e32 v148, v124, v124
	v_mul_f32_e32 v149, v120, v120
	v_fmac_f32_e32 v148, v125, v125
	v_fmac_f32_e32 v149, v121, v121
	v_fmac_f32_e32 v148, v126, v126
	v_fmac_f32_e32 v149, v122, v122
	v_fmac_f32_e32 v148, v127, v127
	v_fmac_f32_e32 v149, v123, v123
	v_fmac_f32_e32 v148, v116, v116
	v_fmac_f32_e32 v149, v112, v112
	v_fmac_f32_e32 v148, v117, v117
	v_fmac_f32_e32 v149, v113, v113
	v_fmac_f32_e32 v148, v118, v118
	v_fmac_f32_e32 v149, v114, v114
	v_fmac_f32_e32 v148, v119, v119
	v_fmac_f32_e32 v149, v115, v115
	s_nop 1
	v_add_f32_dpp v148, v148, v148 row_ror:8 row_mask:0xf bank_mask:0xf
	v_add_f32_dpp v149, v149, v149 row_ror:8 row_mask:0xf bank_mask:0xf
	v_mov_b32_e32 v134, v148
	v_mov_b32_e32 v147, v149
	s_nop 1
	v_permlane16_swap_b32_e32 v148, v134
	v_permlane16_swap_b32_e32 v149, v147
	v_add_f32_e32 v148, v148, v134
	v_add_f32_e32 v149, v149, v147
	v_mov_b32_e32 v134, v148
	v_mov_b32_e32 v147, v149
	s_nop 1
	v_permlane32_swap_b32_e32 v148, v134
	v_permlane32_swap_b32_e32 v149, v147
	v_add_f32_e32 v148, v148, v134
	v_add_f32_e32 v149, v149, v147
	v_cndmask_b32_e32 v148, v148, v149, vcc
	v_lshlrev_b32_e32 v134, 2, v150
	s_mov_b64 exec, s[4:5]
	global_atomic_add_f32 v134, v148, s[50:51]
	s_mov_b64 exec, -1
	v_add_u32_e32 v166, 0x60000, v146
	v_add_u32_e32 v167, 0x70000, v146
	global_load_dwordx4 v[170:173], v166, s[84:85]
	global_load_dwordx4 v[174:177], v167, s[84:85]
	global_load_dwordx4 v[178:181], v166, s[84:85] offset:512
	global_load_dwordx4 v[182:185], v167, s[84:85] offset:512
	v_mov_b32_e32 v158, v104
	v_mov_b32_e32 v159, v105
	v_mov_b32_e32 v160, v106
	v_mov_b32_e32 v161, v107
	v_mov_b32_e32 v162, v96
	v_mov_b32_e32 v163, v97
	v_mov_b32_e32 v164, v98
	v_mov_b32_e32 v165, v99
	v_mov_b32_dpp v104, v108 row_ror:8 row_mask:0xf bank_mask:0x3
	v_mov_b32_dpp v105, v109 row_ror:8 row_mask:0xf bank_mask:0x3
	v_mov_b32_dpp v106, v110 row_ror:8 row_mask:0xf bank_mask:0x3
	v_mov_b32_dpp v107, v111 row_ror:8 row_mask:0xf bank_mask:0x3
	v_mov_b32_dpp v96, v100 row_ror:8 row_mask:0xf bank_mask:0x3
	v_mov_b32_dpp v97, v101 row_ror:8 row_mask:0xf bank_mask:0x3
	v_mov_b32_dpp v98, v102 row_ror:8 row_mask:0xf bank_mask:0x3
	v_mov_b32_dpp v99, v103 row_ror:8 row_mask:0xf bank_mask:0x3
	v_mov_b32_dpp v108, v158 row_ror:8 row_mask:0xf bank_mask:0xc
	v_mov_b32_dpp v109, v159 row_ror:8 row_mask:0xf bank_mask:0xc
	v_mov_b32_dpp v110, v160 row_ror:8 row_mask:0xf bank_mask:0xc
	v_mov_b32_dpp v111, v161 row_ror:8 row_mask:0xf bank_mask:0xc
	v_mov_b32_dpp v100, v162 row_ror:8 row_mask:0xf bank_mask:0xc
	v_mov_b32_dpp v101, v163 row_ror:8 row_mask:0xf bank_mask:0xc
	v_mov_b32_dpp v102, v164 row_ror:8 row_mask:0xf bank_mask:0xc
	v_mov_b32_dpp v103, v165 row_ror:8 row_mask:0xf bank_mask:0xc
	v_add_u32_e32 v166, 0x20000, v146
	v_add_u32_e32 v167, 0x30000, v146
	v_lshrrev_b32_e32 v168, 1, v166
	v_lshrrev_b32_e32 v169, 1, v167
	s_waitcnt vmcnt(17)
	v_pk_add_f32 v[108:109], v[108:109], v[186:187]
	v_pk_add_f32 v[110:111], v[110:111], v[188:189]
	v_pk_add_f32 v[104:105], v[104:105], v[190:191]
	v_pk_add_f32 v[106:107], v[106:107], v[192:193]
	v_pk_add_f32 v[100:101], v[100:101], v[194:195]
	v_pk_add_f32 v[102:103], v[102:103], v[196:197]
	v_pk_add_f32 v[96:97], v[96:97], v[198:199]
	v_pk_add_f32 v[98:99], v[98:99], v[200:201]
	global_store_dwordx4 v166, v[108:111], s[86:87]
	global_store_dwordx4 v167, v[104:107], s[86:87]
	global_store_dwordx4 v166, v[100:103], s[86:87] offset:512
	global_store_dwordx4 v167, v[96:99], s[86:87] offset:512
	v_cvt_pk_bf16_f32 v158, v108, v109
	v_cvt_pk_bf16_f32 v159, v110, v111
	v_cvt_pk_bf16_f32 v160, v104, v105
	v_cvt_pk_bf16_f32 v161, v106, v107
	v_cvt_pk_bf16_f32 v162, v100, v101
	v_cvt_pk_bf16_f32 v163, v102, v103
	v_cvt_pk_bf16_f32 v164, v96, v97
	v_cvt_pk_bf16_f32 v165, v98, v99
	global_store_dwordx2 v168, v[158:159], s[52:53]
	global_store_dwordx2 v169, v[160:161], s[52:53]
	global_store_dwordx2 v168, v[162:163], s[52:53] offset:256
	global_store_dwordx2 v169, v[164:165], s[52:53] offset:256
	v_mul_f32_e32 v148, v108, v108
	v_mul_f32_e32 v149, v104, v104
	v_fmac_f32_e32 v148, v109, v109
	v_fmac_f32_e32 v149, v105, v105
	v_fmac_f32_e32 v148, v110, v110
	v_fmac_f32_e32 v149, v106, v106
	v_fmac_f32_e32 v148, v111, v111
	v_fmac_f32_e32 v149, v107, v107
	v_fmac_f32_e32 v148, v100, v100
	v_fmac_f32_e32 v149, v96, v96
	v_fmac_f32_e32 v148, v101, v101
	v_fmac_f32_e32 v149, v97, v97
	v_fmac_f32_e32 v148, v102, v102
	v_fmac_f32_e32 v149, v98, v98
	v_fmac_f32_e32 v148, v103, v103
	v_fmac_f32_e32 v149, v99, v99
	s_nop 1
	v_add_f32_dpp v148, v148, v148 row_ror:8 row_mask:0xf bank_mask:0xf
	v_add_f32_dpp v149, v149, v149 row_ror:8 row_mask:0xf bank_mask:0xf
	v_mov_b32_e32 v134, v148
	v_mov_b32_e32 v147, v149
	s_nop 1
	v_permlane16_swap_b32_e32 v148, v134
	v_permlane16_swap_b32_e32 v149, v147
	v_add_f32_e32 v148, v148, v134
	v_add_f32_e32 v149, v149, v147
	v_mov_b32_e32 v134, v148
	v_mov_b32_e32 v147, v149
	s_nop 1
	v_permlane32_swap_b32_e32 v148, v134
	v_permlane32_swap_b32_e32 v149, v147
	v_add_f32_e32 v148, v148, v134
	v_add_f32_e32 v149, v149, v147
	v_cndmask_b32_e32 v148, v148, v149, vcc
	v_lshlrev_b32_e32 v134, 2, v150
	s_mov_b64 exec, s[4:5]
	global_atomic_add_f32 v134, v148, s[50:51] offset:64
	s_mov_b64 exec, -1
	v_mov_b32_e32 v158, v88
	v_mov_b32_e32 v159, v89
	v_mov_b32_e32 v160, v90
	v_mov_b32_e32 v161, v91
	v_mov_b32_e32 v162, v80
	v_mov_b32_e32 v163, v81
	v_mov_b32_e32 v164, v82
	v_mov_b32_e32 v165, v83
	v_mov_b32_dpp v88, v92 row_ror:8 row_mask:0xf bank_mask:0x3
	v_mov_b32_dpp v89, v93 row_ror:8 row_mask:0xf bank_mask:0x3
	v_mov_b32_dpp v90, v94 row_ror:8 row_mask:0xf bank_mask:0x3
	v_mov_b32_dpp v91, v95 row_ror:8 row_mask:0xf bank_mask:0x3
	v_mov_b32_dpp v80, v84 row_ror:8 row_mask:0xf bank_mask:0x3
	v_mov_b32_dpp v81, v85 row_ror:8 row_mask:0xf bank_mask:0x3
	v_mov_b32_dpp v82, v86 row_ror:8 row_mask:0xf bank_mask:0x3
	v_mov_b32_dpp v83, v87 row_ror:8 row_mask:0xf bank_mask:0x3
	v_mov_b32_dpp v92, v158 row_ror:8 row_mask:0xf bank_mask:0xc
	v_mov_b32_dpp v93, v159 row_ror:8 row_mask:0xf bank_mask:0xc
	v_mov_b32_dpp v94, v160 row_ror:8 row_mask:0xf bank_mask:0xc
	v_mov_b32_dpp v95, v161 row_ror:8 row_mask:0xf bank_mask:0xc
	v_mov_b32_dpp v84, v162 row_ror:8 row_mask:0xf bank_mask:0xc
	v_mov_b32_dpp v85, v163 row_ror:8 row_mask:0xf bank_mask:0xc
	v_mov_b32_dpp v86, v164 row_ror:8 row_mask:0xf bank_mask:0xc
	v_mov_b32_dpp v87, v165 row_ror:8 row_mask:0xf bank_mask:0xc
	v_add_u32_e32 v166, 0x40000, v146
	v_add_u32_e32 v167, 0x50000, v146
	v_lshrrev_b32_e32 v168, 1, v166
	v_lshrrev_b32_e32 v169, 1, v167
	s_waitcnt vmcnt(22)
	v_pk_add_f32 v[92:93], v[92:93], v[202:203]
	v_pk_add_f32 v[94:95], v[94:95], v[204:205]
	v_pk_add_f32 v[88:89], v[88:89], v[206:207]
	v_pk_add_f32 v[90:91], v[90:91], v[208:209]
	v_pk_add_f32 v[84:85], v[84:85], v[210:211]
	v_pk_add_f32 v[86:87], v[86:87], v[212:213]
	v_pk_add_f32 v[80:81], v[80:81], v[214:215]
	v_pk_add_f32 v[82:83], v[82:83], v[216:217]
	global_store_dwordx4 v166, v[92:95], s[86:87]
	global_store_dwordx4 v167, v[88:91], s[86:87]
	global_store_dwordx4 v166, v[84:87], s[86:87] offset:512
	global_store_dwordx4 v167, v[80:83], s[86:87] offset:512
	v_cvt_pk_bf16_f32 v158, v92, v93
	v_cvt_pk_bf16_f32 v159, v94, v95
	v_cvt_pk_bf16_f32 v160, v88, v89
	v_cvt_pk_bf16_f32 v161, v90, v91
	v_cvt_pk_bf16_f32 v162, v84, v85
	v_cvt_pk_bf16_f32 v163, v86, v87
	v_cvt_pk_bf16_f32 v164, v80, v81
	v_cvt_pk_bf16_f32 v165, v82, v83
	global_store_dwordx2 v168, v[158:159], s[52:53]
	global_store_dwordx2 v169, v[160:161], s[52:53]
	global_store_dwordx2 v168, v[162:163], s[52:53] offset:256
	global_store_dwordx2 v169, v[164:165], s[52:53] offset:256
	v_mul_f32_e32 v148, v92, v92
	v_mul_f32_e32 v149, v88, v88
	v_fmac_f32_e32 v148, v93, v93
	v_fmac_f32_e32 v149, v89, v89
	v_fmac_f32_e32 v148, v94, v94
	v_fmac_f32_e32 v149, v90, v90
	v_fmac_f32_e32 v148, v95, v95
	v_fmac_f32_e32 v149, v91, v91
	v_fmac_f32_e32 v148, v84, v84
	v_fmac_f32_e32 v149, v80, v80
	v_fmac_f32_e32 v148, v85, v85
	v_fmac_f32_e32 v149, v81, v81
	v_fmac_f32_e32 v148, v86, v86
	v_fmac_f32_e32 v149, v82, v82
	v_fmac_f32_e32 v148, v87, v87
	v_fmac_f32_e32 v149, v83, v83
	s_nop 1
	v_add_f32_dpp v148, v148, v148 row_ror:8 row_mask:0xf bank_mask:0xf
	v_add_f32_dpp v149, v149, v149 row_ror:8 row_mask:0xf bank_mask:0xf
	v_mov_b32_e32 v134, v148
	v_mov_b32_e32 v147, v149
	s_nop 1
	v_permlane16_swap_b32_e32 v148, v134
	v_permlane16_swap_b32_e32 v149, v147
	v_add_f32_e32 v148, v148, v134
	v_add_f32_e32 v149, v149, v147
	v_mov_b32_e32 v134, v148
	v_mov_b32_e32 v147, v149
	s_nop 1
	v_permlane32_swap_b32_e32 v148, v134
	v_permlane32_swap_b32_e32 v149, v147
	v_add_f32_e32 v148, v148, v134
	v_add_f32_e32 v149, v149, v147
	v_cndmask_b32_e32 v148, v148, v149, vcc
	v_lshlrev_b32_e32 v134, 2, v150
	s_mov_b64 exec, s[4:5]
	global_atomic_add_f32 v134, v148, s[50:51] offset:128
	s_mov_b64 exec, -1
	v_mov_b32_e32 v158, v72
	v_mov_b32_e32 v159, v73
	v_mov_b32_e32 v160, v74
	v_mov_b32_e32 v161, v75
	v_mov_b32_e32 v162, v64
	v_mov_b32_e32 v163, v65
	v_mov_b32_e32 v164, v66
	v_mov_b32_e32 v165, v67
	v_mov_b32_dpp v72, v76 row_ror:8 row_mask:0xf bank_mask:0x3
	v_mov_b32_dpp v73, v77 row_ror:8 row_mask:0xf bank_mask:0x3
	v_mov_b32_dpp v74, v78 row_ror:8 row_mask:0xf bank_mask:0x3
	v_mov_b32_dpp v75, v79 row_ror:8 row_mask:0xf bank_mask:0x3
	v_mov_b32_dpp v64, v68 row_ror:8 row_mask:0xf bank_mask:0x3
	v_mov_b32_dpp v65, v69 row_ror:8 row_mask:0xf bank_mask:0x3
	v_mov_b32_dpp v66, v70 row_ror:8 row_mask:0xf bank_mask:0x3
	v_mov_b32_dpp v67, v71 row_ror:8 row_mask:0xf bank_mask:0x3
	v_mov_b32_dpp v76, v158 row_ror:8 row_mask:0xf bank_mask:0xc
	v_mov_b32_dpp v77, v159 row_ror:8 row_mask:0xf bank_mask:0xc
	v_mov_b32_dpp v78, v160 row_ror:8 row_mask:0xf bank_mask:0xc
	v_mov_b32_dpp v79, v161 row_ror:8 row_mask:0xf bank_mask:0xc
	v_mov_b32_dpp v68, v162 row_ror:8 row_mask:0xf bank_mask:0xc
	v_mov_b32_dpp v69, v163 row_ror:8 row_mask:0xf bank_mask:0xc
	v_mov_b32_dpp v70, v164 row_ror:8 row_mask:0xf bank_mask:0xc
	v_mov_b32_dpp v71, v165 row_ror:8 row_mask:0xf bank_mask:0xc
	v_add_u32_e32 v166, 0x60000, v146
	v_add_u32_e32 v167, 0x70000, v146
	v_lshrrev_b32_e32 v168, 1, v166
	v_lshrrev_b32_e32 v169, 1, v167
	s_waitcnt vmcnt(18)
	v_pk_add_f32 v[76:77], v[76:77], v[170:171]
	v_pk_add_f32 v[78:79], v[78:79], v[172:173]
	v_pk_add_f32 v[72:73], v[72:73], v[174:175]
	v_pk_add_f32 v[74:75], v[74:75], v[176:177]
	v_pk_add_f32 v[68:69], v[68:69], v[178:179]
	v_pk_add_f32 v[70:71], v[70:71], v[180:181]
	v_pk_add_f32 v[64:65], v[64:65], v[182:183]
	v_pk_add_f32 v[66:67], v[66:67], v[184:185]
	global_store_dwordx4 v166, v[76:79], s[86:87]
	global_store_dwordx4 v167, v[72:75], s[86:87]
	global_store_dwordx4 v166, v[68:71], s[86:87] offset:512
	global_store_dwordx4 v167, v[64:67], s[86:87] offset:512
	v_cvt_pk_bf16_f32 v158, v76, v77
	v_cvt_pk_bf16_f32 v159, v78, v79
	v_cvt_pk_bf16_f32 v160, v72, v73
	v_cvt_pk_bf16_f32 v161, v74, v75
	v_cvt_pk_bf16_f32 v162, v68, v69
	v_cvt_pk_bf16_f32 v163, v70, v71
	v_cvt_pk_bf16_f32 v164, v64, v65
	v_cvt_pk_bf16_f32 v165, v66, v67
	global_store_dwordx2 v168, v[158:159], s[52:53]
	global_store_dwordx2 v169, v[160:161], s[52:53]
	global_store_dwordx2 v168, v[162:163], s[52:53] offset:256
	global_store_dwordx2 v169, v[164:165], s[52:53] offset:256
	v_mul_f32_e32 v148, v76, v76
	v_mul_f32_e32 v149, v72, v72
	v_fmac_f32_e32 v148, v77, v77
	v_fmac_f32_e32 v149, v73, v73
	v_fmac_f32_e32 v148, v78, v78
	v_fmac_f32_e32 v149, v74, v74
	v_fmac_f32_e32 v148, v79, v79
	v_fmac_f32_e32 v149, v75, v75
	v_fmac_f32_e32 v148, v68, v68
	v_fmac_f32_e32 v149, v64, v64
	v_fmac_f32_e32 v148, v69, v69
	v_fmac_f32_e32 v149, v65, v65
	v_fmac_f32_e32 v148, v70, v70
	v_fmac_f32_e32 v149, v66, v66
	v_fmac_f32_e32 v148, v71, v71
	v_fmac_f32_e32 v149, v67, v67
	s_nop 1
	v_add_f32_dpp v148, v148, v148 row_ror:8 row_mask:0xf bank_mask:0xf
	v_add_f32_dpp v149, v149, v149 row_ror:8 row_mask:0xf bank_mask:0xf
	v_mov_b32_e32 v134, v148
	v_mov_b32_e32 v147, v149
	s_nop 1
	v_permlane16_swap_b32_e32 v148, v134
	v_permlane16_swap_b32_e32 v149, v147
	v_add_f32_e32 v148, v148, v134
	v_add_f32_e32 v149, v149, v147
	v_mov_b32_e32 v134, v148
	v_mov_b32_e32 v147, v149
	s_nop 1
	v_permlane32_swap_b32_e32 v148, v134
	v_permlane32_swap_b32_e32 v149, v147
	v_add_f32_e32 v148, v148, v134
	v_add_f32_e32 v149, v149, v147
	v_cndmask_b32_e32 v148, v148, v149, vcc
	v_lshlrev_b32_e32 v134, 2, v150
	s_mov_b64 exec, s[4:5]
	global_atomic_add_f32 v134, v148, s[50:51] offset:192
	s_mov_b64 exec, -1
	s_branch .LBB0_1142
